# GEMM K-loops: the LDS-read wait (lgkmcnt(0)) of each load segment moved from before the segment barrier to its first consumer after it (the compiler's own post-barrier lgkmcnt(0) stays)
# baseline (speedup 1.0000x reference)
; #define PG8_STAGE(bufoff, gbase, voff) do { if constexpr (DIAG >= 1) break; _Pragma("unroll") for (int _i = 0; _i < 2; ++_i) \
;         __builtin_amdgcn_global_load_lds((const unsigned*)((const char*)(gbase) + (voff)[_i]), (PG8_LAS unsigned*)(lds + (bufoff) + ldsw + _i * 8192), 16, 0, 0); } while (0)
; #define PG8_LDA(dst, b, h) do { if constexpr (DIAG == 2 || DIAG == 3) break; _Pragma("unroll") for (int m = 0; m < 4; ++m) _Pragma("unroll") for (int k = 0; k < 2; ++k) dst[m][k] = *(const PG8_LAS bf16x8*)(lds + PG8_SA(b, h) + aoff + m * 2048 + k * 1024); } while (0)
; #define PG8_LDB(dst, b, h) do { if constexpr (DIAG == 2 || DIAG == 3) break; _Pragma("unroll") for (int n = 0; n < 2; ++n) _Pragma("unroll") for (int k = 0; k < 2; ++k) dst[n][k] = *(const PG8_LAS bf16x8*)(lds + PG8_SB(b, h) + boff + n * 2048 + k * 1024); } while (0)
; #define PG8_WAIT_V(n) asm volatile("s_waitcnt vmcnt(" #n ")" ::: "memory")
; #define PG8_WAIT_L(n) asm volatile("s_waitcnt lgkmcnt(" #n ")" ::: "memory")
; #define PG8_BAR __builtin_amdgcn_s_barrier()
; #define PG8_LP_ON __builtin_amdgcn_s_setprio(PG8_LOADPRIO)
; #define PG8_LP_OFF __builtin_amdgcn_s_setprio(0)
; #define PG8_LP_ON do {} while (0)
; #define PG8_LP_OFF do {} while (0)
; #define PG8_SCHED __builtin_amdgcn_sched_barrier(0)
;     ...
;         for (int t = kb; t < ke; t += 2) {
;             const bool last = (t == ke - 2);
;             const char* a1 = cA + (size_t)(t + 1) * kstep;
;             const char* a2 = last ? nA : cA + (size_t)(t + 2) * kstep; const char* b2 = last ? nB : cB + (size_t)(t + 2) * kstep;
;             const char* a3 = a2 + kstep; const char* b3 = b2 + kstep;
;             if (last && has_next) S.a_ready(nxt);
;             if constexpr (SP2) {
;             PG8_LP_ON; PG8_LDB(B0, 0, 0); PG8_LDB(B1, 0, 1); PG8_SCHED; PG8_LDA(At, 0, 0); PG8_STAGE(PG8_SA(1, 1), a1 + hstep, voffA);
;             PG8_LP_OFF; PG8_WAIT_V(8); PG8_WAIT_L(0); PG8_BAR; PG8_MMA(0, 0, At, B0); PG8_MMA(0, 1, At, B1); PG8_BAR; PG8_SCHED;
;             PG8_LP_ON; PG8_LDA(At, 0, 1); PG8_STAGE(PG8_SB(0, 0), b2, voffB); PG8_STAGE(PG8_SB(0, 1), b2 + hstep, voffB); PG8_STAGE(PG8_SA(0, 0), a2, voffA);
;             PG8_LP_OFF; PG8_WAIT_V(8); PG8_WAIT_L(0); PG8_BAR; PG8_MMA(1, 0, At, B0); PG8_MMA(1, 1, At, B1); PG8_BAR; PG8_SCHED;
.LBB0_225:
	ds_read_b128 v[26:29], v192
	ds_read_b128 v[30:33], v192 offset:1024
	ds_read_b128 v[18:21], v192 offset:2048
	ds_read_b128 v[22:25], v192 offset:3072
	ds_read_b128 v[10:13], v193
	ds_read_b128 v[14:17], v193 offset:1024
	ds_read_b128 v[2:5], v193 offset:2048
	ds_read_b128 v[6:9], v193 offset:3072
	s_add_u32 s77, s86, 0xfff80080
	s_addc_u32 s78, s87, -1
	s_cmp_eq_u32 s76, 28
	s_cselect_b32 s91, s23, s78
	s_cselect_b32 s90, vcc_lo, s77
	s_cselect_b32 s89, s21, s75
	s_cselect_b32 s88, vcc_hi, s74
	v_lshl_add_u64 v[220:221], s[86:87], 0, v[174:175]
	s_add_i32 m0, s19, 0xc000
	ds_read_b128 v[182:185], v194
	ds_read_b128 v[186:189], v194 offset:1024
	ds_read_b128 v[196:199], v194 offset:2048
	ds_read_b128 v[200:203], v194 offset:3072
	ds_read_b128 v[204:207], v194 offset:4096
	ds_read_b128 v[208:211], v194 offset:5120
	ds_read_b128 v[212:215], v194 offset:6144
	ds_read_b128 v[216:219], v194 offset:7168
	global_load_lds_dwordx4 v[220:221], off
	v_lshl_add_u64 v[220:221], s[86:87], 0, v[176:177]
	s_add_i32 m0, s19, 0xe000
	s_nop 0
	global_load_lds_dwordx4 v[220:221], off
	s_waitcnt vmcnt(8)
	s_barrier
	s_setprio 1
	s_waitcnt lgkmcnt(0)
	v_mfma_f32_16x16x128_f8f6f4 v[158:161], v[26:33], v[182:189], v[158:161]
	v_mfma_f32_16x16x128_f8f6f4 v[154:157], v[18:25], v[182:189], v[154:157]
	v_mfma_f32_16x16x128_f8f6f4 v[142:145], v[26:33], v[196:203], v[142:145]
	v_mfma_f32_16x16x128_f8f6f4 v[138:141], v[18:25], v[196:203], v[138:141]
	v_mfma_f32_16x16x128_f8f6f4 v[126:129], v[26:33], v[204:211], v[126:129]
	v_mfma_f32_16x16x128_f8f6f4 v[122:125], v[18:25], v[204:211], v[122:125]
	v_mfma_f32_16x16x128_f8f6f4 v[110:113], v[26:33], v[212:219], v[110:113]
	v_mfma_f32_16x16x128_f8f6f4 v[106:109], v[18:25], v[212:219], v[106:109]
	s_setprio 0
	s_setprio 1
	v_mfma_f32_16x16x128_f8f6f4 v[150:153], v[10:17], v[182:189], v[150:153]
	v_mfma_f32_16x16x128_f8f6f4 v[146:149], v[2:9], v[182:189], v[146:149]
	v_mfma_f32_16x16x128_f8f6f4 v[134:137], v[10:17], v[196:203], v[134:137]
	v_mfma_f32_16x16x128_f8f6f4 v[130:133], v[2:9], v[196:203], v[130:133]
	v_mfma_f32_16x16x128_f8f6f4 v[118:121], v[10:17], v[204:211], v[118:121]
	v_mfma_f32_16x16x128_f8f6f4 v[114:117], v[2:9], v[204:211], v[114:117]
	v_mfma_f32_16x16x128_f8f6f4 v[102:105], v[10:17], v[212:219], v[102:105]
	v_mfma_f32_16x16x128_f8f6f4 v[98:101], v[2:9], v[212:219], v[98:101]
	s_setprio 0
	s_barrier
	s_add_i32 s77, s95, s0
	v_lshl_add_u64 v[182:183], s[88:89], 0, v[168:169]
	s_mov_b32 m0, s77
	ds_read_b128 v[196:199], v194 offset:16384
	ds_read_b128 v[200:203], v194 offset:17408
	ds_read_b128 v[204:207], v194 offset:18432
	ds_read_b128 v[208:211], v194 offset:19456
	ds_read_b128 v[212:215], v194 offset:20480
	ds_read_b128 v[216:219], v194 offset:21504
	ds_read_b128 v[220:223], v194 offset:22528
	ds_read_b128 v[224:227], v194 offset:23552
	global_load_lds_dwordx4 v[182:183], off
	s_add_i32 m0, s77, 0x2000
	s_add_u32 s78, s88, 0x80000
	v_lshl_add_u64 v[184:185], s[88:89], 0, v[172:173]
	s_addc_u32 s79, s89, 0
	s_add_i32 s77, s96, s0
	global_load_lds_dwordx4 v[184:185], off
	v_lshl_add_u64 v[186:187], s[78:79], 0, v[168:169]
	s_mov_b32 m0, s77
	v_lshl_add_u64 v[188:189], s[90:91], 0, v[170:171]
	global_load_lds_dwordx4 v[186:187], off
	v_lshl_add_u64 v[186:187], s[78:79], 0, v[172:173]
	s_add_i32 m0, s77, 0x2000
	s_nop 0
	global_load_lds_dwordx4 v[186:187], off
	v_lshl_add_u64 v[186:187], s[90:91], 0, v[166:167]
	s_mov_b32 m0, s19
	s_nop 0
	global_load_lds_dwordx4 v[186:187], off
	s_mov_b32 m0, s34
	s_nop 0
	global_load_lds_dwordx4 v[188:189], off
	s_waitcnt vmcnt(8)
	s_barrier
	s_setprio 1
	s_waitcnt lgkmcnt(0)
	v_mfma_f32_16x16x128_f8f6f4 v[94:97], v[26:33], v[196:203], v[94:97]
	v_mfma_f32_16x16x128_f8f6f4 v[90:93], v[18:25], v[196:203], v[90:93]
	v_mfma_f32_16x16x128_f8f6f4 v[78:81], v[26:33], v[204:211], v[78:81]
	v_mfma_f32_16x16x128_f8f6f4 v[74:77], v[18:25], v[204:211], v[74:77]
	v_mfma_f32_16x16x128_f8f6f4 v[62:65], v[26:33], v[212:219], v[62:65]
	v_mfma_f32_16x16x128_f8f6f4 v[58:61], v[18:25], v[212:219], v[58:61]
	v_mfma_f32_16x16x128_f8f6f4 v[46:49], v[26:33], v[220:227], v[46:49]
	v_mfma_f32_16x16x128_f8f6f4 v[42:45], v[18:25], v[220:227], v[42:45]
	s_setprio 0
	s_setprio 1
	v_mfma_f32_16x16x128_f8f6f4 v[86:89], v[10:17], v[196:203], v[86:89]
	v_mfma_f32_16x16x128_f8f6f4 v[82:85], v[2:9], v[196:203], v[82:85]
	v_mfma_f32_16x16x128_f8f6f4 v[70:73], v[10:17], v[204:211], v[70:73]
	v_mfma_f32_16x16x128_f8f6f4 v[66:69], v[2:9], v[204:211], v[66:69]
	v_mfma_f32_16x16x128_f8f6f4 v[54:57], v[10:17], v[212:219], v[54:57]
	v_mfma_f32_16x16x128_f8f6f4 v[50:53], v[2:9], v[212:219], v[50:53]
	v_mfma_f32_16x16x128_f8f6f4 v[38:41], v[10:17], v[220:227], v[38:41]
	v_mfma_f32_16x16x128_f8f6f4 v[34:37], v[2:9], v[220:227], v[34:37]
	s_setprio 0
	s_barrier
; #define PG8_STAGE(bufoff, gbase, voff) do { if constexpr (DIAG >= 1) break; _Pragma("unroll") for (int _i = 0; _i < 2; ++_i) \
;         __builtin_amdgcn_global_load_lds((const unsigned*)((const char*)(gbase) + (voff)[_i]), (PG8_LAS unsigned*)(lds + (bufoff) + ldsw + _i * 8192), 16, 0, 0); } while (0)
; #define PG8_LDA(dst, b, h) do { if constexpr (DIAG == 2 || DIAG == 3) break; _Pragma("unroll") for (int m = 0; m < 4; ++m) _Pragma("unroll") for (int k = 0; k < 2; ++k) dst[m][k] = *(const PG8_LAS bf16x8*)(lds + PG8_SA(b, h) + aoff + m * 2048 + k * 1024); } while (0)
; #define PG8_LDB(dst, b, h) do { if constexpr (DIAG == 2 || DIAG == 3) break; _Pragma("unroll") for (int n = 0; n < 2; ++n) _Pragma("unroll") for (int k = 0; k < 2; ++k) dst[n][k] = *(const PG8_LAS bf16x8*)(lds + PG8_SB(b, h) + boff + n * 2048 + k * 1024); } while (0)
; #define PG8_WAIT_V(n) asm volatile("s_waitcnt vmcnt(" #n ")" ::: "memory")
; #define PG8_WAIT_L(n) asm volatile("s_waitcnt lgkmcnt(" #n ")" ::: "memory")
; #define PG8_BAR __builtin_amdgcn_s_barrier()
; #define PG8_LP_ON __builtin_amdgcn_s_setprio(PG8_LOADPRIO)
; #define PG8_LP_OFF __builtin_amdgcn_s_setprio(0)
; #define PG8_LP_ON do {} while (0)
; #define PG8_LP_OFF do {} while (0)
; #define PG8_SCHED __builtin_amdgcn_sched_barrier(0)
;     ...
;             PG8_LP_ON; PG8_LDB(B0, 1, 0); PG8_LDB(B1, 1, 1); PG8_SCHED; PG8_LDA(At, 1, 0); PG8_STAGE(PG8_SA(0, 1), a2 + hstep, voffA);
;             PG8_LP_OFF; PG8_WAIT_V(8); PG8_WAIT_L(0); PG8_BAR; PG8_MMA(0, 0, At, B0); PG8_MMA(0, 1, At, B1); PG8_BAR; PG8_SCHED;
;             PG8_LP_ON; PG8_LDA(At, 1, 1); PG8_STAGE(PG8_SB(1, 0), b3, voffB); PG8_STAGE(PG8_SB(1, 1), b3 + hstep, voffB); PG8_STAGE(PG8_SA(1, 0), a3, voffA);
;             PG8_LP_OFF; PG8_WAIT_V(8); PG8_WAIT_L(0); PG8_BAR; PG8_MMA(1, 0, At, B0); PG8_MMA(1, 1, At, B1); PG8_BAR; PG8_SCHED;
;     ...
;         if constexpr (FP8) { asm volatile("s_nop 7\n\ts_nop 7" ::: "memory"); PG8_SCHED; }
	s_add_i32 s77, 0, 0x18000
	s_add_i32 s80, 0, 0x1c000
	v_add_u32_e32 v14, s77, v190
	v_add_u32_e32 v30, s80, v190
	ds_read_b128 v[2:5], v14
	ds_read_b128 v[6:9], v14 offset:1024
	ds_read_b128 v[10:13], v14 offset:2048
	ds_read_b128 v[14:17], v14 offset:3072
	ds_read_b128 v[18:21], v30
	ds_read_b128 v[22:25], v30 offset:1024
	ds_read_b128 v[26:29], v30 offset:2048
	ds_read_b128 v[30:33], v30 offset:3072
	s_add_u32 s78, s90, 0x80000
	s_addc_u32 s79, s91, 0
	s_mov_b32 m0, s73
	v_lshl_add_u64 v[228:229], s[78:79], 0, v[166:167]
	ds_read_b128 v[196:199], v194 offset:32768
	ds_read_b128 v[200:203], v194 offset:33792
	ds_read_b128 v[204:207], v194 offset:34816
	ds_read_b128 v[208:211], v194 offset:35840
	ds_read_b128 v[212:215], v194 offset:36864
	ds_read_b128 v[216:219], v194 offset:37888
	ds_read_b128 v[220:223], v194 offset:38912
	ds_read_b128 v[224:227], v194 offset:39936
	global_load_lds_dwordx4 v[228:229], off
	v_lshl_add_u64 v[228:229], s[78:79], 0, v[170:171]
	s_mov_b32 m0, s84
	s_nop 0
	global_load_lds_dwordx4 v[228:229], off
	s_waitcnt vmcnt(8)
	s_barrier
	s_setprio 1
	s_waitcnt lgkmcnt(0)
	v_mfma_f32_16x16x128_f8f6f4 v[158:161], v[2:9], v[196:203], v[158:161]
	v_mfma_f32_16x16x128_f8f6f4 v[154:157], v[10:17], v[196:203], v[154:157]
	v_mfma_f32_16x16x128_f8f6f4 v[142:145], v[2:9], v[204:211], v[142:145]
	v_mfma_f32_16x16x128_f8f6f4 v[138:141], v[10:17], v[204:211], v[138:141]
	v_mfma_f32_16x16x128_f8f6f4 v[126:129], v[2:9], v[212:219], v[126:129]
	v_mfma_f32_16x16x128_f8f6f4 v[122:125], v[10:17], v[212:219], v[122:125]
	v_mfma_f32_16x16x128_f8f6f4 v[110:113], v[2:9], v[220:227], v[110:113]
	v_mfma_f32_16x16x128_f8f6f4 v[106:109], v[10:17], v[220:227], v[106:109]
	s_setprio 0
	s_setprio 1
	v_mfma_f32_16x16x128_f8f6f4 v[150:153], v[18:25], v[196:203], v[150:153]
	v_mfma_f32_16x16x128_f8f6f4 v[146:149], v[26:33], v[196:203], v[146:149]
	v_mfma_f32_16x16x128_f8f6f4 v[134:137], v[18:25], v[204:211], v[134:137]
	v_mfma_f32_16x16x128_f8f6f4 v[130:133], v[26:33], v[204:211], v[130:133]
	v_mfma_f32_16x16x128_f8f6f4 v[118:121], v[18:25], v[212:219], v[118:121]
	v_mfma_f32_16x16x128_f8f6f4 v[114:117], v[26:33], v[212:219], v[114:117]
	v_mfma_f32_16x16x128_f8f6f4 v[102:105], v[18:25], v[220:227], v[102:105]
	v_mfma_f32_16x16x128_f8f6f4 v[98:101], v[26:33], v[220:227], v[98:101]
	s_setprio 0
	s_barrier
	s_add_i32 s77, s77, s0
	v_lshl_add_u64 v[182:183], v[182:183], 0, s[12:13]
	s_mov_b32 m0, s77
	ds_read_b128 v[196:199], v194 offset:49152
	ds_read_b128 v[200:203], v194 offset:50176
	ds_read_b128 v[204:207], v194 offset:51200
	ds_read_b128 v[208:211], v194 offset:52224
	ds_read_b128 v[212:215], v194 offset:53248
	ds_read_b128 v[216:219], v194 offset:54272
	ds_read_b128 v[220:223], v194 offset:55296
	ds_read_b128 v[224:227], v194 offset:56320
	global_load_lds_dwordx4 v[182:183], off
	s_add_i32 m0, s77, 0x2000
	s_add_u32 s78, s88, 0x80080
	v_lshl_add_u64 v[182:183], v[184:185], 0, s[12:13]
	s_addc_u32 s79, s89, 0
	s_add_i32 s77, s80, s0
	global_load_lds_dwordx4 v[182:183], off
	v_lshl_add_u64 v[182:183], s[78:79], 0, v[168:169]
	s_mov_b32 m0, s77
	s_nop 0
	global_load_lds_dwordx4 v[182:183], off
	v_lshl_add_u64 v[182:183], s[78:79], 0, v[172:173]
	s_add_i32 m0, s77, 0x2000
	s_nop 0
	global_load_lds_dwordx4 v[182:183], off
	v_lshl_add_u64 v[182:183], v[186:187], 0, s[12:13]
	s_mov_b32 m0, s93
	s_nop 0
	global_load_lds_dwordx4 v[182:183], off
	v_lshl_add_u64 v[182:183], v[188:189], 0, s[12:13]
	s_mov_b32 m0, s94
	s_nop 0
	global_load_lds_dwordx4 v[182:183], off
	s_waitcnt vmcnt(8)
	s_barrier
	s_setprio 1
	s_waitcnt lgkmcnt(0)
	v_mfma_f32_16x16x128_f8f6f4 v[94:97], v[2:9], v[196:203], v[94:97]
	v_mfma_f32_16x16x128_f8f6f4 v[90:93], v[10:17], v[196:203], v[90:93]
	v_mfma_f32_16x16x128_f8f6f4 v[78:81], v[2:9], v[204:211], v[78:81]
	v_mfma_f32_16x16x128_f8f6f4 v[74:77], v[10:17], v[204:211], v[74:77]
	v_mfma_f32_16x16x128_f8f6f4 v[62:65], v[2:9], v[212:219], v[62:65]
	v_mfma_f32_16x16x128_f8f6f4 v[58:61], v[10:17], v[212:219], v[58:61]
	v_mfma_f32_16x16x128_f8f6f4 v[46:49], v[2:9], v[220:227], v[46:49]
	v_mfma_f32_16x16x128_f8f6f4 v[42:45], v[10:17], v[220:227], v[42:45]
	s_setprio 0
	s_setprio 1
	v_mfma_f32_16x16x128_f8f6f4 v[86:89], v[18:25], v[196:203], v[86:89]
	v_mfma_f32_16x16x128_f8f6f4 v[82:85], v[26:33], v[196:203], v[82:85]
	v_mfma_f32_16x16x128_f8f6f4 v[70:73], v[18:25], v[204:211], v[70:73]
	v_mfma_f32_16x16x128_f8f6f4 v[66:69], v[26:33], v[204:211], v[66:69]
	v_mfma_f32_16x16x128_f8f6f4 v[54:57], v[18:25], v[212:219], v[54:57]
	v_mfma_f32_16x16x128_f8f6f4 v[50:53], v[26:33], v[212:219], v[50:53]
	v_mfma_f32_16x16x128_f8f6f4 v[38:41], v[18:25], v[220:227], v[38:41]
	v_mfma_f32_16x16x128_f8f6f4 v[34:37], v[26:33], v[220:227], v[34:37]
	s_setprio 0
	s_barrier
	s_add_i32 s76, s76, 2
	s_add_u32 s86, s86, 0x100
	s_addc_u32 s87, s87, 0
	s_add_u32 s74, s74, 0x100
	s_addc_u32 s75, s75, 0
	s_cmp_gt_u32 s76, 29
	s_cbranch_scc0 .LBB0_225
	s_nop 7
	s_nop 7
	s_and_b64 vcc, exec, s[14:15]
	s_cbranch_vccz .LBB0_228
	s_barrier

; #define PG8_STAGE(bufoff, gbase, voff) do { if constexpr (DIAG >= 1) break; _Pragma("unroll") for (int _i = 0; _i < 2; ++_i) \
;         __builtin_amdgcn_global_load_lds((const unsigned*)((const char*)(gbase) + (voff)[_i]), (PG8_LAS unsigned*)(lds + (bufoff) + ldsw + _i * 8192), 16, 0, 0); } while (0)
; #define PG8_LDA(dst, b, h) do { if constexpr (DIAG == 2 || DIAG == 3) break; _Pragma("unroll") for (int m = 0; m < 4; ++m) _Pragma("unroll") for (int k = 0; k < 2; ++k) dst[m][k] = *(const PG8_LAS bf16x8*)(lds + PG8_SA(b, h) + aoff + m * 2048 + k * 1024); } while (0)
; #define PG8_LDB(dst, b, h) do { if constexpr (DIAG == 2 || DIAG == 3) break; _Pragma("unroll") for (int n = 0; n < 2; ++n) _Pragma("unroll") for (int k = 0; k < 2; ++k) dst[n][k] = *(const PG8_LAS bf16x8*)(lds + PG8_SB(b, h) + boff + n * 2048 + k * 1024); } while (0)
; #define PG8_WAIT_V(n) asm volatile("s_waitcnt vmcnt(" #n ")" ::: "memory")
; #define PG8_WAIT_L(n) asm volatile("s_waitcnt lgkmcnt(" #n ")" ::: "memory")
; #define PG8_BAR __builtin_amdgcn_s_barrier()
; #define PG8_LP_ON __builtin_amdgcn_s_setprio(PG8_LOADPRIO)
; #define PG8_LP_OFF __builtin_amdgcn_s_setprio(0)
; #define PG8_LP_ON do {} while (0)
; #define PG8_LP_OFF do {} while (0)
; #define PG8_SCHED __builtin_amdgcn_sched_barrier(0)
;     ...
;         for (int t = kb; t < ke; t += 2) {
;             const bool last = (t == ke - 2);
;             const char* a1 = cA + (size_t)(t + 1) * kstep;
;             const char* a2 = last ? nA : cA + (size_t)(t + 2) * kstep; const char* b2 = last ? nB : cB + (size_t)(t + 2) * kstep;
;             const char* a3 = a2 + kstep; const char* b3 = b2 + kstep;
;             if (last && has_next) S.a_ready(nxt);
;             if constexpr (SP2) {
;             PG8_LP_ON; PG8_LDB(B0, 0, 0); PG8_LDB(B1, 0, 1); PG8_SCHED; PG8_LDA(At, 0, 0); PG8_STAGE(PG8_SA(1, 1), a1 + hstep, voffA);
;             PG8_LP_OFF; PG8_WAIT_V(8); PG8_WAIT_L(0); PG8_BAR; PG8_MMA(0, 0, At, B0); PG8_MMA(0, 1, At, B1); PG8_BAR; PG8_SCHED;
;             PG8_LP_ON; PG8_LDA(At, 0, 1); PG8_STAGE(PG8_SB(0, 0), b2, voffB); PG8_STAGE(PG8_SB(0, 1), b2 + hstep, voffB); PG8_STAGE(PG8_SA(0, 0), a2, voffA);
;             PG8_LP_OFF; PG8_WAIT_V(8); PG8_WAIT_L(0); PG8_BAR; PG8_MMA(1, 0, At, B0); PG8_MMA(1, 1, At, B1); PG8_BAR; PG8_SCHED;
.LBB0_306:
	ds_read_b128 v[26:29], v200
	ds_read_b128 v[30:33], v200 offset:1024
	ds_read_b128 v[18:21], v200 offset:2048
	ds_read_b128 v[22:25], v200 offset:3072
	ds_read_b128 v[10:13], v201
	ds_read_b128 v[14:17], v201 offset:1024
	ds_read_b128 v[2:5], v201 offset:2048
	ds_read_b128 v[6:9], v201 offset:3072
	s_add_u32 s74, s4, 0xffea8080
	s_addc_u32 s75, s5, -1
	s_cmpk_eq_i32 s77, 0x52
	s_cselect_b32 s87, s23, s75
	s_cselect_b32 s86, s22, s74
	s_cselect_b32 s75, s73, s76
	s_cselect_b32 s74, s72, s27
	v_lshl_add_u64 v[196:197], s[4:5], 0, v[172:173]
	s_add_i32 m0, s84, 0xc000
	ds_read_b128 v[180:183], v202
	ds_read_b128 v[184:187], v202 offset:1024
	ds_read_b128 v[188:191], v202 offset:2048
	ds_read_b128 v[192:195], v202 offset:3072
	ds_read_b128 v[204:207], v202 offset:4096
	ds_read_b128 v[208:211], v202 offset:5120
	ds_read_b128 v[212:215], v202 offset:6144
	ds_read_b128 v[216:219], v202 offset:7168
	global_load_lds_dwordx4 v[196:197], off
	v_lshl_add_u64 v[196:197], s[4:5], 0, v[174:175]
	s_add_i32 m0, s84, 0xe000
	s_nop 0
	global_load_lds_dwordx4 v[196:197], off
	s_waitcnt vmcnt(8)
	s_barrier
	s_setprio 1
	s_waitcnt lgkmcnt(0)
	v_mfma_f32_16x16x128_f8f6f4 v[158:161], v[26:33], v[180:187], v[158:161]
	v_mfma_f32_16x16x128_f8f6f4 v[154:157], v[18:25], v[180:187], v[154:157]
	v_mfma_f32_16x16x128_f8f6f4 v[142:145], v[26:33], v[188:195], v[142:145]
	v_mfma_f32_16x16x128_f8f6f4 v[138:141], v[18:25], v[188:195], v[138:141]
	v_mfma_f32_16x16x128_f8f6f4 v[126:129], v[26:33], v[204:211], v[126:129]
	v_mfma_f32_16x16x128_f8f6f4 v[122:125], v[18:25], v[204:211], v[122:125]
	v_mfma_f32_16x16x128_f8f6f4 v[110:113], v[26:33], v[212:219], v[110:113]
	v_mfma_f32_16x16x128_f8f6f4 v[106:109], v[18:25], v[212:219], v[106:109]
	s_setprio 0
	s_setprio 1
	v_mfma_f32_16x16x128_f8f6f4 v[150:153], v[10:17], v[180:187], v[150:153]
	v_mfma_f32_16x16x128_f8f6f4 v[146:149], v[2:9], v[180:187], v[146:149]
	v_mfma_f32_16x16x128_f8f6f4 v[134:137], v[10:17], v[188:195], v[134:137]
	v_mfma_f32_16x16x128_f8f6f4 v[130:133], v[2:9], v[188:195], v[130:133]
	v_mfma_f32_16x16x128_f8f6f4 v[118:121], v[10:17], v[204:211], v[118:121]
	v_mfma_f32_16x16x128_f8f6f4 v[114:117], v[2:9], v[204:211], v[114:117]
	v_mfma_f32_16x16x128_f8f6f4 v[102:105], v[10:17], v[212:219], v[102:105]
	v_mfma_f32_16x16x128_f8f6f4 v[98:101], v[2:9], v[212:219], v[98:101]
	s_setprio 0
	s_barrier
	s_add_i32 s78, s96, s21
	v_lshl_add_u64 v[180:181], s[74:75], 0, v[166:167]
	s_mov_b32 m0, s78
	ds_read_b128 v[188:191], v202 offset:16384
	ds_read_b128 v[192:195], v202 offset:17408
	ds_read_b128 v[204:207], v202 offset:18432
	ds_read_b128 v[208:211], v202 offset:19456
	ds_read_b128 v[212:215], v202 offset:20480
	ds_read_b128 v[216:219], v202 offset:21504
	ds_read_b128 v[220:223], v202 offset:22528
	ds_read_b128 v[224:227], v202 offset:23552
	global_load_lds_dwordx4 v[180:181], off
	s_add_i32 m0, s78, 0x2000
	s_add_u32 s78, s74, 0x158000
	v_lshl_add_u64 v[182:183], s[74:75], 0, v[168:169]
	s_addc_u32 s79, s75, 0
	s_add_i32 s80, s97, s21
	global_load_lds_dwordx4 v[182:183], off
	v_lshl_add_u64 v[184:185], s[78:79], 0, v[166:167]
	s_mov_b32 m0, s80
	v_lshl_add_u64 v[186:187], s[86:87], 0, v[168:169]
	global_load_lds_dwordx4 v[184:185], off
	v_lshl_add_u64 v[184:185], s[78:79], 0, v[168:169]
	s_add_i32 m0, s80, 0x2000
	s_nop 0
	global_load_lds_dwordx4 v[184:185], off
	v_lshl_add_u64 v[184:185], s[86:87], 0, v[166:167]
	s_mov_b32 m0, s84
	s_nop 0
	global_load_lds_dwordx4 v[184:185], off
	s_mov_b32 m0, s85
	s_nop 0
	global_load_lds_dwordx4 v[186:187], off
	s_waitcnt vmcnt(8)
	s_barrier
	s_setprio 1
	s_waitcnt lgkmcnt(0)
	v_mfma_f32_16x16x128_f8f6f4 v[94:97], v[26:33], v[188:195], v[94:97]
	v_mfma_f32_16x16x128_f8f6f4 v[90:93], v[18:25], v[188:195], v[90:93]
	v_mfma_f32_16x16x128_f8f6f4 v[78:81], v[26:33], v[204:211], v[78:81]
	v_mfma_f32_16x16x128_f8f6f4 v[74:77], v[18:25], v[204:211], v[74:77]
	v_mfma_f32_16x16x128_f8f6f4 v[62:65], v[26:33], v[212:219], v[62:65]
	v_mfma_f32_16x16x128_f8f6f4 v[58:61], v[18:25], v[212:219], v[58:61]
	v_mfma_f32_16x16x128_f8f6f4 v[46:49], v[26:33], v[220:227], v[46:49]
	v_mfma_f32_16x16x128_f8f6f4 v[42:45], v[18:25], v[220:227], v[42:45]
	s_setprio 0
	s_setprio 1
	v_mfma_f32_16x16x128_f8f6f4 v[86:89], v[10:17], v[188:195], v[86:89]
	v_mfma_f32_16x16x128_f8f6f4 v[82:85], v[2:9], v[188:195], v[82:85]
	v_mfma_f32_16x16x128_f8f6f4 v[70:73], v[10:17], v[204:211], v[70:73]
	v_mfma_f32_16x16x128_f8f6f4 v[66:69], v[2:9], v[204:211], v[66:69]
	v_mfma_f32_16x16x128_f8f6f4 v[54:57], v[10:17], v[212:219], v[54:57]
	v_mfma_f32_16x16x128_f8f6f4 v[50:53], v[2:9], v[212:219], v[50:53]
	v_mfma_f32_16x16x128_f8f6f4 v[38:41], v[10:17], v[220:227], v[38:41]
	v_mfma_f32_16x16x128_f8f6f4 v[34:37], v[2:9], v[220:227], v[34:37]
	s_setprio 0
	s_barrier
; #define PG8_STAGE(bufoff, gbase, voff) do { if constexpr (DIAG >= 1) break; _Pragma("unroll") for (int _i = 0; _i < 2; ++_i) \
;         __builtin_amdgcn_global_load_lds((const unsigned*)((const char*)(gbase) + (voff)[_i]), (PG8_LAS unsigned*)(lds + (bufoff) + ldsw + _i * 8192), 16, 0, 0); } while (0)
; #define PG8_LDA(dst, b, h) do { if constexpr (DIAG == 2 || DIAG == 3) break; _Pragma("unroll") for (int m = 0; m < 4; ++m) _Pragma("unroll") for (int k = 0; k < 2; ++k) dst[m][k] = *(const PG8_LAS bf16x8*)(lds + PG8_SA(b, h) + aoff + m * 2048 + k * 1024); } while (0)
; #define PG8_LDB(dst, b, h) do { if constexpr (DIAG == 2 || DIAG == 3) break; _Pragma("unroll") for (int n = 0; n < 2; ++n) _Pragma("unroll") for (int k = 0; k < 2; ++k) dst[n][k] = *(const PG8_LAS bf16x8*)(lds + PG8_SB(b, h) + boff + n * 2048 + k * 1024); } while (0)
; #define PG8_WAIT_V(n) asm volatile("s_waitcnt vmcnt(" #n ")" ::: "memory")
; #define PG8_WAIT_L(n) asm volatile("s_waitcnt lgkmcnt(" #n ")" ::: "memory")
; #define PG8_BAR __builtin_amdgcn_s_barrier()
; #define PG8_LP_ON __builtin_amdgcn_s_setprio(PG8_LOADPRIO)
; #define PG8_LP_OFF __builtin_amdgcn_s_setprio(0)
; #define PG8_LP_ON do {} while (0)
; #define PG8_LP_OFF do {} while (0)
; #define PG8_SCHED __builtin_amdgcn_sched_barrier(0)
;     ...
;             PG8_LP_ON; PG8_LDB(B0, 1, 0); PG8_LDB(B1, 1, 1); PG8_SCHED; PG8_LDA(At, 1, 0); PG8_STAGE(PG8_SA(0, 1), a2 + hstep, voffA);
;             PG8_LP_OFF; PG8_WAIT_V(8); PG8_WAIT_L(0); PG8_BAR; PG8_MMA(0, 0, At, B0); PG8_MMA(0, 1, At, B1); PG8_BAR; PG8_SCHED;
;             PG8_LP_ON; PG8_LDA(At, 1, 1); PG8_STAGE(PG8_SB(1, 0), b3, voffB); PG8_STAGE(PG8_SB(1, 1), b3 + hstep, voffB); PG8_STAGE(PG8_SA(1, 0), a3, voffA);
;             PG8_LP_OFF; PG8_WAIT_V(8); PG8_WAIT_L(0); PG8_BAR; PG8_MMA(1, 0, At, B0); PG8_MMA(1, 1, At, B1); PG8_BAR; PG8_SCHED;
;     ...
;         if constexpr (FP8) { asm volatile("s_nop 7\n\ts_nop 7" ::: "memory"); PG8_SCHED; }
	s_add_i32 s80, 0, 0x18000
	s_add_i32 s81, 0, 0x1c000
	v_add_u32_e32 v14, s80, v198
	v_add_u32_e32 v30, s81, v198
	ds_read_b128 v[2:5], v14
	ds_read_b128 v[6:9], v14 offset:1024
	ds_read_b128 v[10:13], v14 offset:2048
	ds_read_b128 v[14:17], v14 offset:3072
	ds_read_b128 v[18:21], v30
	ds_read_b128 v[22:25], v30 offset:1024
	ds_read_b128 v[26:29], v30 offset:2048
	ds_read_b128 v[30:33], v30 offset:3072
	s_add_u32 s78, s86, 0x158000
	s_addc_u32 s79, s87, 0
	s_mov_b32 m0, s88
	v_lshl_add_u64 v[196:197], s[78:79], 0, v[166:167]
	ds_read_b128 v[188:191], v202 offset:32768
	ds_read_b128 v[192:195], v202 offset:33792
	ds_read_b128 v[204:207], v202 offset:34816
	ds_read_b128 v[208:211], v202 offset:35840
	ds_read_b128 v[212:215], v202 offset:36864
	ds_read_b128 v[216:219], v202 offset:37888
	ds_read_b128 v[220:223], v202 offset:38912
	ds_read_b128 v[224:227], v202 offset:39936
	global_load_lds_dwordx4 v[196:197], off
	v_lshl_add_u64 v[196:197], s[78:79], 0, v[168:169]
	s_mov_b32 m0, s89
	s_nop 0
	global_load_lds_dwordx4 v[196:197], off
	s_waitcnt vmcnt(8)
	s_barrier
	s_setprio 1
	s_waitcnt lgkmcnt(0)
	v_mfma_f32_16x16x128_f8f6f4 v[158:161], v[2:9], v[188:195], v[158:161]
	v_mfma_f32_16x16x128_f8f6f4 v[154:157], v[10:17], v[188:195], v[154:157]
	v_mfma_f32_16x16x128_f8f6f4 v[142:145], v[2:9], v[204:211], v[142:145]
	v_mfma_f32_16x16x128_f8f6f4 v[138:141], v[10:17], v[204:211], v[138:141]
	v_mfma_f32_16x16x128_f8f6f4 v[126:129], v[2:9], v[212:219], v[126:129]
	v_mfma_f32_16x16x128_f8f6f4 v[122:125], v[10:17], v[212:219], v[122:125]
	v_mfma_f32_16x16x128_f8f6f4 v[110:113], v[2:9], v[220:227], v[110:113]
	v_mfma_f32_16x16x128_f8f6f4 v[106:109], v[10:17], v[220:227], v[106:109]
	s_setprio 0
	s_setprio 1
	v_mfma_f32_16x16x128_f8f6f4 v[150:153], v[18:25], v[188:195], v[150:153]
	v_mfma_f32_16x16x128_f8f6f4 v[146:149], v[26:33], v[188:195], v[146:149]
	v_mfma_f32_16x16x128_f8f6f4 v[134:137], v[18:25], v[204:211], v[134:137]
	v_mfma_f32_16x16x128_f8f6f4 v[130:133], v[26:33], v[204:211], v[130:133]
	v_mfma_f32_16x16x128_f8f6f4 v[118:121], v[18:25], v[212:219], v[118:121]
	v_mfma_f32_16x16x128_f8f6f4 v[114:117], v[26:33], v[212:219], v[114:117]
	v_mfma_f32_16x16x128_f8f6f4 v[102:105], v[18:25], v[220:227], v[102:105]
	v_mfma_f32_16x16x128_f8f6f4 v[98:101], v[26:33], v[220:227], v[98:101]
	s_setprio 0
	s_barrier
	s_add_i32 s78, s80, s21
	v_lshl_add_u64 v[180:181], v[180:181], 0, s[14:15]
	s_mov_b32 m0, s78
	ds_read_b128 v[188:191], v202 offset:49152
	ds_read_b128 v[192:195], v202 offset:50176
	ds_read_b128 v[204:207], v202 offset:51200
	ds_read_b128 v[208:211], v202 offset:52224
	ds_read_b128 v[212:215], v202 offset:53248
	ds_read_b128 v[216:219], v202 offset:54272
	ds_read_b128 v[220:223], v202 offset:55296
	ds_read_b128 v[224:227], v202 offset:56320
	global_load_lds_dwordx4 v[180:181], off
	s_add_i32 m0, s78, 0x2000
	s_add_u32 s74, s74, 0x158080
	v_lshl_add_u64 v[180:181], v[182:183], 0, s[14:15]
	s_addc_u32 s75, s75, 0
	s_add_i32 s78, s81, s21
	global_load_lds_dwordx4 v[180:181], off
	v_lshl_add_u64 v[180:181], s[74:75], 0, v[166:167]
	s_mov_b32 m0, s78
	s_nop 0
	global_load_lds_dwordx4 v[180:181], off
	v_lshl_add_u64 v[180:181], s[74:75], 0, v[168:169]
	s_add_i32 m0, s78, 0x2000
	s_nop 0
	global_load_lds_dwordx4 v[180:181], off
	v_lshl_add_u64 v[180:181], v[184:185], 0, s[14:15]
	s_mov_b32 m0, s94
	s_nop 0
	global_load_lds_dwordx4 v[180:181], off
	v_lshl_add_u64 v[180:181], v[186:187], 0, s[14:15]
	s_mov_b32 m0, s95
	s_nop 0
	global_load_lds_dwordx4 v[180:181], off
	s_waitcnt vmcnt(8)
	s_barrier
	s_setprio 1
	s_waitcnt lgkmcnt(0)
	v_mfma_f32_16x16x128_f8f6f4 v[94:97], v[2:9], v[188:195], v[94:97]
	v_mfma_f32_16x16x128_f8f6f4 v[90:93], v[10:17], v[188:195], v[90:93]
	v_mfma_f32_16x16x128_f8f6f4 v[78:81], v[2:9], v[204:211], v[78:81]
	v_mfma_f32_16x16x128_f8f6f4 v[74:77], v[10:17], v[204:211], v[74:77]
	v_mfma_f32_16x16x128_f8f6f4 v[62:65], v[2:9], v[212:219], v[62:65]
	v_mfma_f32_16x16x128_f8f6f4 v[58:61], v[10:17], v[212:219], v[58:61]
	v_mfma_f32_16x16x128_f8f6f4 v[46:49], v[2:9], v[220:227], v[46:49]
	v_mfma_f32_16x16x128_f8f6f4 v[42:45], v[10:17], v[220:227], v[42:45]
	s_setprio 0
	s_setprio 1
	v_mfma_f32_16x16x128_f8f6f4 v[86:89], v[18:25], v[188:195], v[86:89]
	v_mfma_f32_16x16x128_f8f6f4 v[82:85], v[26:33], v[188:195], v[82:85]
	v_mfma_f32_16x16x128_f8f6f4 v[70:73], v[18:25], v[204:211], v[70:73]
	v_mfma_f32_16x16x128_f8f6f4 v[66:69], v[26:33], v[204:211], v[66:69]
	v_mfma_f32_16x16x128_f8f6f4 v[54:57], v[18:25], v[212:219], v[54:57]
	v_mfma_f32_16x16x128_f8f6f4 v[50:53], v[26:33], v[212:219], v[50:53]
	v_mfma_f32_16x16x128_f8f6f4 v[38:41], v[18:25], v[220:227], v[38:41]
	v_mfma_f32_16x16x128_f8f6f4 v[34:37], v[26:33], v[220:227], v[34:37]
	s_setprio 0
	s_barrier
	s_add_i32 s77, s77, 2
	s_add_u32 s4, s4, 0x100
	s_addc_u32 s5, s5, 0
	s_add_u32 s27, s27, 0x100
	s_addc_u32 s76, s76, 0
	s_cmpk_gt_u32 s77, 0x53
	s_cbranch_scc0 .LBB0_306
	s_nop 7
	s_nop 7
	s_and_b64 vcc, exec, s[16:17]
	s_cbranch_vccz .LBB0_309
	s_barrier

; #define PG8_STAGE(bufoff, gbase, voff) do { if constexpr (DIAG >= 1) break; _Pragma("unroll") for (int _i = 0; _i < 2; ++_i) \
;         __builtin_amdgcn_global_load_lds((const unsigned*)((const char*)(gbase) + (voff)[_i]), (PG8_LAS unsigned*)(lds + (bufoff) + ldsw + _i * 8192), 16, 0, 0); } while (0)
; #define PG8_LDA(dst, b, h) do { if constexpr (DIAG == 2 || DIAG == 3) break; _Pragma("unroll") for (int m = 0; m < 4; ++m) _Pragma("unroll") for (int k = 0; k < 2; ++k) dst[m][k] = *(const PG8_LAS bf16x8*)(lds + PG8_SA(b, h) + aoff + m * 2048 + k * 1024); } while (0)
; #define PG8_LDB(dst, b, h) do { if constexpr (DIAG == 2 || DIAG == 3) break; _Pragma("unroll") for (int n = 0; n < 2; ++n) _Pragma("unroll") for (int k = 0; k < 2; ++k) dst[n][k] = *(const PG8_LAS bf16x8*)(lds + PG8_SB(b, h) + boff + n * 2048 + k * 1024); } while (0)
; #define PG8_WAIT_V(n) asm volatile("s_waitcnt vmcnt(" #n ")" ::: "memory")
; #define PG8_WAIT_L(n) asm volatile("s_waitcnt lgkmcnt(" #n ")" ::: "memory")
; #define PG8_BAR __builtin_amdgcn_s_barrier()
; #define PG8_LP_ON __builtin_amdgcn_s_setprio(PG8_LOADPRIO)
; #define PG8_LP_OFF __builtin_amdgcn_s_setprio(0)
; #define PG8_LP_ON do {} while (0)
; #define PG8_LP_OFF do {} while (0)
; #define PG8_SCHED __builtin_amdgcn_sched_barrier(0)
;     ...
;         for (int t = kb; t < ke; t += 2) {
;             const bool last = (t == ke - 2);
;             const char* a1 = cA + (size_t)(t + 1) * kstep;
;             const char* a2 = last ? nA : cA + (size_t)(t + 2) * kstep; const char* b2 = last ? nB : cB + (size_t)(t + 2) * kstep;
;             const char* a3 = a2 + kstep; const char* b3 = b2 + kstep;
;             if (last && has_next) S.a_ready(nxt);
;             if constexpr (SP2) {
;             PG8_LP_ON; PG8_LDB(B0, 0, 0); PG8_LDB(B1, 0, 1); PG8_SCHED; PG8_LDA(At, 0, 0); PG8_STAGE(PG8_SA(1, 1), a1 + hstep, voffA);
;             PG8_LP_OFF; PG8_WAIT_V(8); PG8_WAIT_L(0); PG8_BAR; PG8_MMA(0, 0, At, B0); PG8_MMA(0, 1, At, B1); PG8_BAR; PG8_SCHED;
;             PG8_LP_ON; PG8_LDA(At, 0, 1); PG8_STAGE(PG8_SB(0, 0), b2, voffB); PG8_STAGE(PG8_SB(0, 1), b2 + hstep, voffB); PG8_STAGE(PG8_SA(0, 0), a2, voffA);
;             PG8_LP_OFF; PG8_WAIT_V(8); PG8_WAIT_L(0); PG8_BAR; PG8_MMA(1, 0, At, B0); PG8_MMA(1, 1, At, B1); PG8_BAR; PG8_SCHED;
.LBB0_505:
	ds_read_b128 v[26:29], v205
	ds_read_b128 v[30:33], v205 offset:1024
	ds_read_b128 v[18:21], v205 offset:2048
	ds_read_b128 v[22:25], v205 offset:3072
	ds_read_b128 v[10:13], v206
	ds_read_b128 v[14:17], v206 offset:1024
	ds_read_b128 v[2:5], v206 offset:2048
	ds_read_b128 v[6:9], v206 offset:3072
	s_add_u32 s76, s74, 0xfff80080
	s_addc_u32 s77, s75, -1
	s_cmp_eq_u32 s82, 28
	s_cselect_b32 s79, s19, s77
	s_cselect_b32 s78, s95, s76
	s_cselect_b32 s77, s17, s81
	s_cselect_b32 s76, s96, s80
	v_lshl_add_u64 v[232:233], s[74:75], 0, v[174:175]
	s_add_i32 m0, s55, 0xc000
	ds_read_b128 v[182:185], v207
	ds_read_b128 v[186:189], v207 offset:1024
	ds_read_b128 v[208:211], v207 offset:2048
	ds_read_b128 v[212:215], v207 offset:3072
	ds_read_b128 v[216:219], v207 offset:4096
	ds_read_b128 v[220:223], v207 offset:5120
	ds_read_b128 v[224:227], v207 offset:6144
	ds_read_b128 v[228:231], v207 offset:7168
	global_load_lds_dwordx4 v[232:233], off
	v_lshl_add_u64 v[232:233], s[74:75], 0, v[176:177]
	s_add_i32 m0, s55, 0xe000
	s_nop 0
	global_load_lds_dwordx4 v[232:233], off
	s_waitcnt vmcnt(8)
	s_barrier
	s_setprio 1
	s_waitcnt lgkmcnt(0)
	v_mfma_f32_16x16x128_f8f6f4 v[158:161], v[26:33], v[182:189], v[158:161]
	v_mfma_f32_16x16x128_f8f6f4 v[154:157], v[18:25], v[182:189], v[154:157]
	v_mfma_f32_16x16x128_f8f6f4 v[146:149], v[26:33], v[208:215], v[146:149]
	v_mfma_f32_16x16x128_f8f6f4 v[138:141], v[18:25], v[208:215], v[138:141]
	v_mfma_f32_16x16x128_f8f6f4 v[130:133], v[26:33], v[216:223], v[130:133]
	v_mfma_f32_16x16x128_f8f6f4 v[122:125], v[18:25], v[216:223], v[122:125]
	v_mfma_f32_16x16x128_f8f6f4 v[114:117], v[26:33], v[224:231], v[114:117]
	v_mfma_f32_16x16x128_f8f6f4 v[106:109], v[18:25], v[224:231], v[106:109]
	s_setprio 0
	s_setprio 1
	v_mfma_f32_16x16x128_f8f6f4 v[150:153], v[10:17], v[182:189], v[150:153]
	v_mfma_f32_16x16x128_f8f6f4 v[142:145], v[2:9], v[182:189], v[142:145]
	v_mfma_f32_16x16x128_f8f6f4 v[134:137], v[10:17], v[208:215], v[134:137]
	v_mfma_f32_16x16x128_f8f6f4 v[126:129], v[2:9], v[208:215], v[126:129]
	v_mfma_f32_16x16x128_f8f6f4 v[118:121], v[10:17], v[216:223], v[118:121]
	v_mfma_f32_16x16x128_f8f6f4 v[110:113], v[2:9], v[216:223], v[110:113]
	v_mfma_f32_16x16x128_f8f6f4 v[102:105], v[10:17], v[224:231], v[102:105]
	v_mfma_f32_16x16x128_f8f6f4 v[98:101], v[2:9], v[224:231], v[98:101]
	s_setprio 0
	s_barrier
	s_add_i32 s83, s92, s86
	v_lshl_add_u64 v[182:183], s[76:77], 0, v[168:169]
	s_mov_b32 m0, s83
	ds_read_b128 v[208:211], v207 offset:16384
	ds_read_b128 v[212:215], v207 offset:17408
	ds_read_b128 v[216:219], v207 offset:18432
	ds_read_b128 v[220:223], v207 offset:19456
	ds_read_b128 v[224:227], v207 offset:20480
	ds_read_b128 v[228:231], v207 offset:21504
	ds_read_b128 v[232:235], v207 offset:22528
	ds_read_b128 v[236:239], v207 offset:23552
	global_load_lds_dwordx4 v[182:183], off
	s_add_i32 m0, s83, 0x2000
	s_add_u32 vcc_lo, s76, 0x80000
	v_lshl_add_u64 v[184:185], s[76:77], 0, v[172:173]
	s_addc_u32 vcc_hi, s77, 0
	s_add_i32 s83, s93, s86
	global_load_lds_dwordx4 v[184:185], off
	v_lshl_add_u64 v[186:187], vcc, 0, v[168:169]
	s_mov_b32 m0, s83
	v_lshl_add_u64 v[188:189], s[78:79], 0, v[170:171]
	global_load_lds_dwordx4 v[186:187], off
	v_lshl_add_u64 v[186:187], vcc, 0, v[172:173]
	s_add_i32 m0, s83, 0x2000
	s_nop 0
	global_load_lds_dwordx4 v[186:187], off
	v_lshl_add_u64 v[186:187], s[78:79], 0, v[166:167]
	s_mov_b32 m0, s55
	s_nop 0
	global_load_lds_dwordx4 v[186:187], off
	s_mov_b32 m0, s73
	s_nop 0
	global_load_lds_dwordx4 v[188:189], off
	s_waitcnt vmcnt(8)
	s_barrier
	s_setprio 1
	s_waitcnt lgkmcnt(0)
	v_mfma_f32_16x16x128_f8f6f4 v[94:97], v[26:33], v[208:215], v[94:97]
	v_mfma_f32_16x16x128_f8f6f4 v[90:93], v[18:25], v[208:215], v[90:93]
	v_mfma_f32_16x16x128_f8f6f4 v[82:85], v[26:33], v[216:223], v[82:85]
	v_mfma_f32_16x16x128_f8f6f4 v[74:77], v[18:25], v[216:223], v[74:77]
	v_mfma_f32_16x16x128_f8f6f4 v[66:69], v[26:33], v[224:231], v[66:69]
	v_mfma_f32_16x16x128_f8f6f4 v[58:61], v[18:25], v[224:231], v[58:61]
	v_mfma_f32_16x16x128_f8f6f4 v[50:53], v[26:33], v[232:239], v[50:53]
	v_mfma_f32_16x16x128_f8f6f4 v[42:45], v[18:25], v[232:239], v[42:45]
	s_setprio 0
	s_setprio 1
	v_mfma_f32_16x16x128_f8f6f4 v[86:89], v[10:17], v[208:215], v[86:89]
	v_mfma_f32_16x16x128_f8f6f4 v[78:81], v[2:9], v[208:215], v[78:81]
	v_mfma_f32_16x16x128_f8f6f4 v[70:73], v[10:17], v[216:223], v[70:73]
	v_mfma_f32_16x16x128_f8f6f4 v[62:65], v[2:9], v[216:223], v[62:65]
	v_mfma_f32_16x16x128_f8f6f4 v[54:57], v[10:17], v[224:231], v[54:57]
	v_mfma_f32_16x16x128_f8f6f4 v[46:49], v[2:9], v[224:231], v[46:49]
	v_mfma_f32_16x16x128_f8f6f4 v[38:41], v[10:17], v[232:239], v[38:41]
	v_mfma_f32_16x16x128_f8f6f4 v[34:37], v[2:9], v[232:239], v[34:37]
	s_setprio 0
	s_barrier
; #define PG8_STAGE(bufoff, gbase, voff) do { if constexpr (DIAG >= 1) break; _Pragma("unroll") for (int _i = 0; _i < 2; ++_i) \
;         __builtin_amdgcn_global_load_lds((const unsigned*)((const char*)(gbase) + (voff)[_i]), (PG8_LAS unsigned*)(lds + (bufoff) + ldsw + _i * 8192), 16, 0, 0); } while (0)
; #define PG8_LDA(dst, b, h) do { if constexpr (DIAG == 2 || DIAG == 3) break; _Pragma("unroll") for (int m = 0; m < 4; ++m) _Pragma("unroll") for (int k = 0; k < 2; ++k) dst[m][k] = *(const PG8_LAS bf16x8*)(lds + PG8_SA(b, h) + aoff + m * 2048 + k * 1024); } while (0)
; #define PG8_LDB(dst, b, h) do { if constexpr (DIAG == 2 || DIAG == 3) break; _Pragma("unroll") for (int n = 0; n < 2; ++n) _Pragma("unroll") for (int k = 0; k < 2; ++k) dst[n][k] = *(const PG8_LAS bf16x8*)(lds + PG8_SB(b, h) + boff + n * 2048 + k * 1024); } while (0)
; #define PG8_WAIT_V(n) asm volatile("s_waitcnt vmcnt(" #n ")" ::: "memory")
; #define PG8_WAIT_L(n) asm volatile("s_waitcnt lgkmcnt(" #n ")" ::: "memory")
; #define PG8_BAR __builtin_amdgcn_s_barrier()
; #define PG8_LP_ON __builtin_amdgcn_s_setprio(PG8_LOADPRIO)
; #define PG8_LP_OFF __builtin_amdgcn_s_setprio(0)
; #define PG8_LP_ON do {} while (0)
; #define PG8_LP_OFF do {} while (0)
; #define PG8_SCHED __builtin_amdgcn_sched_barrier(0)
;     ...
;             PG8_LP_ON; PG8_LDB(B0, 1, 0); PG8_LDB(B1, 1, 1); PG8_SCHED; PG8_LDA(At, 1, 0); PG8_STAGE(PG8_SA(0, 1), a2 + hstep, voffA);
;             PG8_LP_OFF; PG8_WAIT_V(8); PG8_WAIT_L(0); PG8_BAR; PG8_MMA(0, 0, At, B0); PG8_MMA(0, 1, At, B1); PG8_BAR; PG8_SCHED;
;             PG8_LP_ON; PG8_LDA(At, 1, 1); PG8_STAGE(PG8_SB(1, 0), b3, voffB); PG8_STAGE(PG8_SB(1, 1), b3 + hstep, voffB); PG8_STAGE(PG8_SA(1, 0), a3, voffA);
;             PG8_LP_OFF; PG8_WAIT_V(8); PG8_WAIT_L(0); PG8_BAR; PG8_MMA(1, 0, At, B0); PG8_MMA(1, 1, At, B1); PG8_BAR; PG8_SCHED;
;     ...
;         if constexpr (FP8) { asm volatile("s_nop 7\n\ts_nop 7" ::: "memory"); PG8_SCHED; }
	s_add_i32 s83, 0, 0x18000
	s_add_i32 s97, 0, 0x1c000
	v_add_u32_e32 v14, s83, v203
	v_add_u32_e32 v30, s97, v203
	ds_read_b128 v[2:5], v14
	ds_read_b128 v[6:9], v14 offset:1024
	ds_read_b128 v[10:13], v14 offset:2048
	ds_read_b128 v[14:17], v14 offset:3072
	ds_read_b128 v[18:21], v30
	ds_read_b128 v[22:25], v30 offset:1024
	ds_read_b128 v[26:29], v30 offset:2048
	ds_read_b128 v[30:33], v30 offset:3072
	s_add_u32 s78, s78, 0x80000
	s_addc_u32 s79, s79, 0
	s_mov_b32 m0, s87
	v_lshl_add_u64 v[240:241], s[78:79], 0, v[166:167]
	ds_read_b128 v[208:211], v207 offset:32768
	ds_read_b128 v[212:215], v207 offset:33792
	ds_read_b128 v[216:219], v207 offset:34816
	ds_read_b128 v[220:223], v207 offset:35840
	ds_read_b128 v[224:227], v207 offset:36864
	ds_read_b128 v[228:231], v207 offset:37888
	ds_read_b128 v[232:235], v207 offset:38912
	ds_read_b128 v[236:239], v207 offset:39936
	global_load_lds_dwordx4 v[240:241], off
	v_lshl_add_u64 v[240:241], s[78:79], 0, v[170:171]
	s_mov_b32 m0, s88
	s_nop 0
	global_load_lds_dwordx4 v[240:241], off
	s_waitcnt vmcnt(8)
	s_barrier
	s_setprio 1
	s_waitcnt lgkmcnt(0)
	v_mfma_f32_16x16x128_f8f6f4 v[158:161], v[2:9], v[208:215], v[158:161]
	v_mfma_f32_16x16x128_f8f6f4 v[154:157], v[10:17], v[208:215], v[154:157]
	v_mfma_f32_16x16x128_f8f6f4 v[146:149], v[2:9], v[216:223], v[146:149]
	v_mfma_f32_16x16x128_f8f6f4 v[138:141], v[10:17], v[216:223], v[138:141]
	v_mfma_f32_16x16x128_f8f6f4 v[130:133], v[2:9], v[224:231], v[130:133]
	v_mfma_f32_16x16x128_f8f6f4 v[122:125], v[10:17], v[224:231], v[122:125]
	v_mfma_f32_16x16x128_f8f6f4 v[114:117], v[2:9], v[232:239], v[114:117]
	v_mfma_f32_16x16x128_f8f6f4 v[106:109], v[10:17], v[232:239], v[106:109]
	s_setprio 0
	s_setprio 1
	v_mfma_f32_16x16x128_f8f6f4 v[150:153], v[18:25], v[208:215], v[150:153]
	v_mfma_f32_16x16x128_f8f6f4 v[142:145], v[26:33], v[208:215], v[142:145]
	v_mfma_f32_16x16x128_f8f6f4 v[134:137], v[18:25], v[216:223], v[134:137]
	v_mfma_f32_16x16x128_f8f6f4 v[126:129], v[26:33], v[216:223], v[126:129]
	v_mfma_f32_16x16x128_f8f6f4 v[118:121], v[18:25], v[224:231], v[118:121]
	v_mfma_f32_16x16x128_f8f6f4 v[110:113], v[26:33], v[224:231], v[110:113]
	v_mfma_f32_16x16x128_f8f6f4 v[102:105], v[18:25], v[232:239], v[102:105]
	v_mfma_f32_16x16x128_f8f6f4 v[98:101], v[26:33], v[232:239], v[98:101]
	s_setprio 0
	s_barrier
	s_add_i32 s78, s83, s86
	v_lshl_add_u64 v[182:183], v[182:183], 0, s[10:11]
	s_mov_b32 m0, s78
	ds_read_b128 v[208:211], v207 offset:49152
	ds_read_b128 v[212:215], v207 offset:50176
	ds_read_b128 v[216:219], v207 offset:51200
	ds_read_b128 v[220:223], v207 offset:52224
	ds_read_b128 v[224:227], v207 offset:53248
	ds_read_b128 v[228:231], v207 offset:54272
	ds_read_b128 v[232:235], v207 offset:55296
	ds_read_b128 v[236:239], v207 offset:56320
	global_load_lds_dwordx4 v[182:183], off
	s_add_i32 m0, s78, 0x2000
	s_add_u32 s76, s76, 0x80080
	v_lshl_add_u64 v[182:183], v[184:185], 0, s[10:11]
	s_addc_u32 s77, s77, 0
	s_add_i32 s78, s97, s86
	global_load_lds_dwordx4 v[182:183], off
	v_lshl_add_u64 v[182:183], s[76:77], 0, v[168:169]
	s_mov_b32 m0, s78
	s_nop 0
	global_load_lds_dwordx4 v[182:183], off
	v_lshl_add_u64 v[182:183], s[76:77], 0, v[172:173]
	s_add_i32 m0, s78, 0x2000
	s_nop 0
	global_load_lds_dwordx4 v[182:183], off
	v_lshl_add_u64 v[182:183], v[186:187], 0, s[10:11]
	s_mov_b32 m0, s89
	s_nop 0
	global_load_lds_dwordx4 v[182:183], off
	v_lshl_add_u64 v[182:183], v[188:189], 0, s[10:11]
	s_mov_b32 m0, s90
	s_nop 0
	global_load_lds_dwordx4 v[182:183], off
	s_waitcnt vmcnt(8)
	s_barrier
	s_setprio 1
	s_waitcnt lgkmcnt(0)
	v_mfma_f32_16x16x128_f8f6f4 v[94:97], v[2:9], v[208:215], v[94:97]
	v_mfma_f32_16x16x128_f8f6f4 v[90:93], v[10:17], v[208:215], v[90:93]
	v_mfma_f32_16x16x128_f8f6f4 v[82:85], v[2:9], v[216:223], v[82:85]
	v_mfma_f32_16x16x128_f8f6f4 v[74:77], v[10:17], v[216:223], v[74:77]
	v_mfma_f32_16x16x128_f8f6f4 v[66:69], v[2:9], v[224:231], v[66:69]
	v_mfma_f32_16x16x128_f8f6f4 v[58:61], v[10:17], v[224:231], v[58:61]
	v_mfma_f32_16x16x128_f8f6f4 v[50:53], v[2:9], v[232:239], v[50:53]
	v_mfma_f32_16x16x128_f8f6f4 v[42:45], v[10:17], v[232:239], v[42:45]
	s_setprio 0
	s_setprio 1
	v_mfma_f32_16x16x128_f8f6f4 v[86:89], v[18:25], v[208:215], v[86:89]
	v_mfma_f32_16x16x128_f8f6f4 v[78:81], v[26:33], v[208:215], v[78:81]
	v_mfma_f32_16x16x128_f8f6f4 v[70:73], v[18:25], v[216:223], v[70:73]
	v_mfma_f32_16x16x128_f8f6f4 v[62:65], v[26:33], v[216:223], v[62:65]
	v_mfma_f32_16x16x128_f8f6f4 v[54:57], v[18:25], v[224:231], v[54:57]
	v_mfma_f32_16x16x128_f8f6f4 v[46:49], v[26:33], v[224:231], v[46:49]
	v_mfma_f32_16x16x128_f8f6f4 v[38:41], v[18:25], v[232:239], v[38:41]
	v_mfma_f32_16x16x128_f8f6f4 v[34:37], v[26:33], v[232:239], v[34:37]
	s_setprio 0
	s_barrier
	s_add_i32 s82, s82, 2
	s_add_u32 s74, s74, 0x100
	s_addc_u32 s75, s75, 0
	s_add_u32 s80, s80, 0x100
	s_addc_u32 s81, s81, 0
	s_cmp_gt_u32 s82, 29
	s_cbranch_scc0 .LBB0_505
	s_nop 7
	s_nop 7
	s_and_b64 vcc, exec, s[12:13]
	s_cbranch_vccz .LBB0_508
	s_barrier

; #define PG8_STAGE(bufoff, gbase, voff) do { if constexpr (DIAG >= 1) break; _Pragma("unroll") for (int _i = 0; _i < 2; ++_i) \
;         __builtin_amdgcn_global_load_lds((const unsigned*)((const char*)(gbase) + (voff)[_i]), (PG8_LAS unsigned*)(lds + (bufoff) + ldsw + _i * 8192), 16, 0, 0); } while (0)
; #define PG8_LDA(dst, b, h) do { if constexpr (DIAG == 2 || DIAG == 3) break; _Pragma("unroll") for (int m = 0; m < 4; ++m) _Pragma("unroll") for (int k = 0; k < 2; ++k) dst[m][k] = *(const PG8_LAS bf16x8*)(lds + PG8_SA(b, h) + aoff + m * 2048 + k * 1024); } while (0)
; #define PG8_LDB(dst, b, h) do { if constexpr (DIAG == 2 || DIAG == 3) break; _Pragma("unroll") for (int n = 0; n < 2; ++n) _Pragma("unroll") for (int k = 0; k < 2; ++k) dst[n][k] = *(const PG8_LAS bf16x8*)(lds + PG8_SB(b, h) + boff + n * 2048 + k * 1024); } while (0)
; #define PG8_WAIT_V(n) asm volatile("s_waitcnt vmcnt(" #n ")" ::: "memory")
; #define PG8_WAIT_L(n) asm volatile("s_waitcnt lgkmcnt(" #n ")" ::: "memory")
; #define PG8_BAR __builtin_amdgcn_s_barrier()
; #define PG8_LP_ON __builtin_amdgcn_s_setprio(PG8_LOADPRIO)
; #define PG8_LP_OFF __builtin_amdgcn_s_setprio(0)
; #define PG8_LP_ON do {} while (0)
; #define PG8_LP_OFF do {} while (0)
; #define PG8_SCHED __builtin_amdgcn_sched_barrier(0)
;     ...
;         for (int t = kb; t < ke; t += 2) {
;             const bool last = (t == ke - 2);
;             const char* a1 = cA + (size_t)(t + 1) * kstep;
;             const char* a2 = last ? nA : cA + (size_t)(t + 2) * kstep; const char* b2 = last ? nB : cB + (size_t)(t + 2) * kstep;
;             const char* a3 = a2 + kstep; const char* b3 = b2 + kstep;
;             if (last && has_next) S.a_ready(nxt);
;             if constexpr (SP2) {
;             PG8_LP_ON; PG8_LDB(B0, 0, 0); PG8_LDB(B1, 0, 1); PG8_SCHED; PG8_LDA(At, 0, 0); PG8_STAGE(PG8_SA(1, 1), a1 + hstep, voffA);
;             PG8_LP_OFF; PG8_WAIT_V(8); PG8_WAIT_L(0); PG8_BAR; PG8_MMA(0, 0, At, B0); PG8_MMA(0, 1, At, B1); PG8_BAR; PG8_SCHED;
;             PG8_LP_ON; PG8_LDA(At, 0, 1); PG8_STAGE(PG8_SB(0, 0), b2, voffB); PG8_STAGE(PG8_SB(0, 1), b2 + hstep, voffB); PG8_STAGE(PG8_SA(0, 0), a2, voffA);
;             PG8_LP_OFF; PG8_WAIT_V(8); PG8_WAIT_L(0); PG8_BAR; PG8_MMA(1, 0, At, B0); PG8_MMA(1, 1, At, B1); PG8_BAR; PG8_SCHED;
.LBB0_521:
	ds_read_b128 v[146:149], v153
	ds_read_b128 v[156:159], v153 offset:1024
	ds_read_b128 v[166:169], v153 offset:2048
	ds_read_b128 v[170:173], v153 offset:3072
	ds_read_b128 v[174:177], v154
	ds_read_b128 v[178:181], v154 offset:1024
	ds_read_b128 v[182:185], v154 offset:2048
	ds_read_b128 v[186:189], v154 offset:3072
	s_add_u32 s74, s72, 0xfff00080
	s_addc_u32 s75, s73, -1
	s_cmp_eq_u32 s91, 60
	s_cselect_b32 s77, s17, s75
	s_cselect_b32 s76, s80, s74
	s_cselect_b32 s75, s15, s83
	s_cselect_b32 s74, s81, s82
	v_lshl_add_u64 v[160:161], s[72:73], 0, v[138:139]
	s_add_i32 m0, s23, 0xc000
	ds_read_b128 v[192:195], v155
	ds_read_b128 v[196:199], v155 offset:1024
	ds_read_b128 v[200:203], v155 offset:2048
	ds_read_b128 v[204:207], v155 offset:3072
	ds_read_b128 v[208:211], v155 offset:4096
	ds_read_b128 v[212:215], v155 offset:5120
	ds_read_b128 v[216:219], v155 offset:6144
	ds_read_b128 v[220:223], v155 offset:7168
	global_load_lds_dwordx4 v[160:161], off
	v_lshl_add_u64 v[160:161], s[72:73], 0, v[140:141]
	s_add_i32 m0, s23, 0xe000
	s_nop 0
	global_load_lds_dwordx4 v[160:161], off
	s_waitcnt vmcnt(8)
	s_barrier
	s_setprio 1
	s_waitcnt lgkmcnt(0)
	v_mfma_f32_16x16x32_bf16 v[126:129], v[146:149], v[192:195], v[126:129]
	v_mfma_f32_16x16x32_bf16 v[122:125], v[166:169], v[192:195], v[122:125]
	v_mfma_f32_16x16x32_bf16 v[118:121], v[146:149], v[200:203], v[118:121]
	v_mfma_f32_16x16x32_bf16 v[110:113], v[166:169], v[200:203], v[110:113]
	v_mfma_f32_16x16x32_bf16 v[102:105], v[146:149], v[208:211], v[102:105]
	v_mfma_f32_16x16x32_bf16 v[94:97], v[166:169], v[208:211], v[94:97]
	v_mfma_f32_16x16x32_bf16 v[86:89], v[146:149], v[216:219], v[86:89]
	v_mfma_f32_16x16x32_bf16 v[78:81], v[166:169], v[216:219], v[78:81]
	v_mfma_f32_16x16x32_bf16 v[126:129], v[156:159], v[196:199], v[126:129]
	v_mfma_f32_16x16x32_bf16 v[122:125], v[170:173], v[196:199], v[122:125]
	v_mfma_f32_16x16x32_bf16 v[118:121], v[156:159], v[204:207], v[118:121]
	v_mfma_f32_16x16x32_bf16 v[110:113], v[170:173], v[204:207], v[110:113]
	v_mfma_f32_16x16x32_bf16 v[102:105], v[156:159], v[212:215], v[102:105]
	v_mfma_f32_16x16x32_bf16 v[94:97], v[170:173], v[212:215], v[94:97]
	v_mfma_f32_16x16x32_bf16 v[86:89], v[156:159], v[220:223], v[86:89]
	v_mfma_f32_16x16x32_bf16 v[78:81], v[170:173], v[220:223], v[78:81]
	s_setprio 0
	s_setprio 1
	v_mfma_f32_16x16x32_bf16 v[114:117], v[174:177], v[192:195], v[114:117]
	v_mfma_f32_16x16x32_bf16 v[106:109], v[182:185], v[192:195], v[106:109]
	v_mfma_f32_16x16x32_bf16 v[98:101], v[174:177], v[200:203], v[98:101]
	v_mfma_f32_16x16x32_bf16 v[90:93], v[182:185], v[200:203], v[90:93]
	v_mfma_f32_16x16x32_bf16 v[82:85], v[174:177], v[208:211], v[82:85]
	v_mfma_f32_16x16x32_bf16 v[74:77], v[182:185], v[208:211], v[74:77]
	v_mfma_f32_16x16x32_bf16 v[70:73], v[174:177], v[216:219], v[70:73]
	v_mfma_f32_16x16x32_bf16 v[66:69], v[182:185], v[216:219], v[66:69]
	v_mfma_f32_16x16x32_bf16 v[114:117], v[178:181], v[196:199], v[114:117]
	v_mfma_f32_16x16x32_bf16 v[106:109], v[186:189], v[196:199], v[106:109]
	v_mfma_f32_16x16x32_bf16 v[98:101], v[178:181], v[204:207], v[98:101]
	v_mfma_f32_16x16x32_bf16 v[90:93], v[186:189], v[204:207], v[90:93]
	v_mfma_f32_16x16x32_bf16 v[82:85], v[178:181], v[212:215], v[82:85]
	v_mfma_f32_16x16x32_bf16 v[74:77], v[186:189], v[212:215], v[74:77]
	v_mfma_f32_16x16x32_bf16 v[70:73], v[178:181], v[220:223], v[70:73]
	v_mfma_f32_16x16x32_bf16 v[66:69], v[186:189], v[220:223], v[66:69]
	s_setprio 0
	s_barrier
	s_add_i32 s92, s88, s27
	v_lshl_add_u64 v[160:161], s[74:75], 0, v[132:133]
	s_mov_b32 m0, s92
	ds_read_b128 v[192:195], v155 offset:16384
	ds_read_b128 v[196:199], v155 offset:17408
	ds_read_b128 v[200:203], v155 offset:18432
	ds_read_b128 v[204:207], v155 offset:19456
	ds_read_b128 v[208:211], v155 offset:20480
	ds_read_b128 v[212:215], v155 offset:21504
	ds_read_b128 v[216:219], v155 offset:22528
	ds_read_b128 v[220:223], v155 offset:23552
	global_load_lds_dwordx4 v[160:161], off
	s_add_i32 m0, s92, 0x2000
	s_add_u32 s92, s74, 0x100000
	v_lshl_add_u64 v[224:225], s[74:75], 0, v[136:137]
	s_addc_u32 s93, s75, 0
	s_add_i32 s94, s89, s27
	global_load_lds_dwordx4 v[224:225], off
	v_lshl_add_u64 v[226:227], s[92:93], 0, v[132:133]
	s_mov_b32 m0, s94
	v_lshl_add_u64 v[228:229], s[76:77], 0, v[134:135]
	global_load_lds_dwordx4 v[226:227], off
	v_lshl_add_u64 v[226:227], s[92:93], 0, v[136:137]
	s_add_i32 m0, s94, 0x2000
	s_nop 0
	global_load_lds_dwordx4 v[226:227], off
	v_lshl_add_u64 v[226:227], s[76:77], 0, v[130:131]
	s_mov_b32 m0, s23
	s_nop 0
	global_load_lds_dwordx4 v[226:227], off
	s_mov_b32 m0, s26
	s_nop 0
	global_load_lds_dwordx4 v[228:229], off
	s_waitcnt vmcnt(8)
	s_barrier
; #define PG8_STAGE(bufoff, gbase, voff) do { if constexpr (DIAG >= 1) break; _Pragma("unroll") for (int _i = 0; _i < 2; ++_i) \
;         __builtin_amdgcn_global_load_lds((const unsigned*)((const char*)(gbase) + (voff)[_i]), (PG8_LAS unsigned*)(lds + (bufoff) + ldsw + _i * 8192), 16, 0, 0); } while (0)
; #define PG8_LDA(dst, b, h) do { if constexpr (DIAG == 2 || DIAG == 3) break; _Pragma("unroll") for (int m = 0; m < 4; ++m) _Pragma("unroll") for (int k = 0; k < 2; ++k) dst[m][k] = *(const PG8_LAS bf16x8*)(lds + PG8_SA(b, h) + aoff + m * 2048 + k * 1024); } while (0)
; #define PG8_LDB(dst, b, h) do { if constexpr (DIAG == 2 || DIAG == 3) break; _Pragma("unroll") for (int n = 0; n < 2; ++n) _Pragma("unroll") for (int k = 0; k < 2; ++k) dst[n][k] = *(const PG8_LAS bf16x8*)(lds + PG8_SB(b, h) + boff + n * 2048 + k * 1024); } while (0)
; #define PG8_WAIT_V(n) asm volatile("s_waitcnt vmcnt(" #n ")" ::: "memory")
; #define PG8_WAIT_L(n) asm volatile("s_waitcnt lgkmcnt(" #n ")" ::: "memory")
; #define PG8_BAR __builtin_amdgcn_s_barrier()
; #define PG8_LP_ON __builtin_amdgcn_s_setprio(PG8_LOADPRIO)
; #define PG8_LP_OFF __builtin_amdgcn_s_setprio(0)
; #define PG8_LP_ON do {} while (0)
; #define PG8_LP_OFF do {} while (0)
; #define PG8_SCHED __builtin_amdgcn_sched_barrier(0)
;     ...
;             PG8_LP_OFF; PG8_WAIT_V(8); PG8_WAIT_L(0); PG8_BAR; PG8_MMA(1, 0, At, B0); PG8_MMA(1, 1, At, B1); PG8_BAR; PG8_SCHED;
;             PG8_LP_ON; PG8_LDB(B0, 1, 0); PG8_LDB(B1, 1, 1); PG8_SCHED; PG8_LDA(At, 1, 0); PG8_STAGE(PG8_SA(0, 1), a2 + hstep, voffA);
;             PG8_LP_OFF; PG8_WAIT_V(8); PG8_WAIT_L(0); PG8_BAR; PG8_MMA(0, 0, At, B0); PG8_MMA(0, 1, At, B1); PG8_BAR; PG8_SCHED;
	s_setprio 1
	s_waitcnt lgkmcnt(0)
	v_mfma_f32_16x16x32_bf16 v[62:65], v[146:149], v[192:195], v[62:65]
	v_mfma_f32_16x16x32_bf16 v[58:61], v[166:169], v[192:195], v[58:61]
	v_mfma_f32_16x16x32_bf16 v[54:57], v[146:149], v[200:203], v[54:57]
	v_mfma_f32_16x16x32_bf16 v[46:49], v[166:169], v[200:203], v[46:49]
	v_mfma_f32_16x16x32_bf16 v[38:41], v[146:149], v[208:211], v[38:41]
	v_mfma_f32_16x16x32_bf16 v[30:33], v[166:169], v[208:211], v[30:33]
	v_mfma_f32_16x16x32_bf16 v[22:25], v[146:149], v[216:219], v[22:25]
	v_mfma_f32_16x16x32_bf16 v[14:17], v[166:169], v[216:219], v[14:17]
	v_mfma_f32_16x16x32_bf16 v[62:65], v[156:159], v[196:199], v[62:65]
	v_mfma_f32_16x16x32_bf16 v[58:61], v[170:173], v[196:199], v[58:61]
	v_mfma_f32_16x16x32_bf16 v[54:57], v[156:159], v[204:207], v[54:57]
	v_mfma_f32_16x16x32_bf16 v[46:49], v[170:173], v[204:207], v[46:49]
	v_mfma_f32_16x16x32_bf16 v[38:41], v[156:159], v[212:215], v[38:41]
	v_mfma_f32_16x16x32_bf16 v[30:33], v[170:173], v[212:215], v[30:33]
	v_mfma_f32_16x16x32_bf16 v[22:25], v[156:159], v[220:223], v[22:25]
	v_mfma_f32_16x16x32_bf16 v[14:17], v[170:173], v[220:223], v[14:17]
	s_setprio 0
	s_setprio 1
	v_mfma_f32_16x16x32_bf16 v[50:53], v[174:177], v[192:195], v[50:53]
	v_mfma_f32_16x16x32_bf16 v[42:45], v[182:185], v[192:195], v[42:45]
	v_mfma_f32_16x16x32_bf16 v[34:37], v[174:177], v[200:203], v[34:37]
	v_mfma_f32_16x16x32_bf16 v[26:29], v[182:185], v[200:203], v[26:29]
	v_mfma_f32_16x16x32_bf16 v[18:21], v[174:177], v[208:211], v[18:21]
	v_mfma_f32_16x16x32_bf16 v[10:13], v[182:185], v[208:211], v[10:13]
	v_mfma_f32_16x16x32_bf16 v[6:9], v[174:177], v[216:219], v[6:9]
	v_mfma_f32_16x16x32_bf16 v[2:5], v[182:185], v[216:219], v[2:5]
	v_mfma_f32_16x16x32_bf16 v[50:53], v[178:181], v[196:199], v[50:53]
	v_mfma_f32_16x16x32_bf16 v[42:45], v[186:189], v[196:199], v[42:45]
	v_mfma_f32_16x16x32_bf16 v[34:37], v[178:181], v[204:207], v[34:37]
	v_mfma_f32_16x16x32_bf16 v[26:29], v[186:189], v[204:207], v[26:29]
	v_mfma_f32_16x16x32_bf16 v[18:21], v[178:181], v[212:215], v[18:21]
	v_mfma_f32_16x16x32_bf16 v[10:13], v[186:189], v[212:215], v[10:13]
	v_mfma_f32_16x16x32_bf16 v[6:9], v[178:181], v[220:223], v[6:9]
	v_mfma_f32_16x16x32_bf16 v[2:5], v[186:189], v[220:223], v[2:5]
	s_setprio 0
	s_barrier
	s_add_i32 s92, 0, 0x18000
	v_add_u32_e32 v165, s92, v151
	s_add_i32 s93, 0, 0x1c000
	ds_read_b128 v[146:149], v165
	ds_read_b128 v[156:159], v165 offset:1024
	ds_read_b128 v[166:169], v165 offset:2048
	ds_read_b128 v[170:173], v165 offset:3072
	v_add_u32_e32 v165, s93, v151
	ds_read_b128 v[174:177], v165
	ds_read_b128 v[178:181], v165 offset:1024
	ds_read_b128 v[182:185], v165 offset:2048
	ds_read_b128 v[186:189], v165 offset:3072
	s_add_u32 s76, s76, 0x100000
	s_addc_u32 s77, s77, 0
	s_mov_b32 m0, s55
	v_lshl_add_u64 v[230:231], s[76:77], 0, v[130:131]
	ds_read_b128 v[192:195], v155 offset:32768
	ds_read_b128 v[196:199], v155 offset:33792
	ds_read_b128 v[200:203], v155 offset:34816
	ds_read_b128 v[204:207], v155 offset:35840
	ds_read_b128 v[208:211], v155 offset:36864
	ds_read_b128 v[212:215], v155 offset:37888
	ds_read_b128 v[216:219], v155 offset:38912
	ds_read_b128 v[220:223], v155 offset:39936
	global_load_lds_dwordx4 v[230:231], off
	v_lshl_add_u64 v[230:231], s[76:77], 0, v[134:135]
	s_mov_b32 m0, s84
	s_nop 0
	global_load_lds_dwordx4 v[230:231], off
	s_waitcnt vmcnt(8)
	s_barrier
	s_setprio 1
	s_waitcnt lgkmcnt(0)
	v_mfma_f32_16x16x32_bf16 v[126:129], v[146:149], v[192:195], v[126:129]
	v_mfma_f32_16x16x32_bf16 v[122:125], v[166:169], v[192:195], v[122:125]
	v_mfma_f32_16x16x32_bf16 v[118:121], v[146:149], v[200:203], v[118:121]
	v_mfma_f32_16x16x32_bf16 v[110:113], v[166:169], v[200:203], v[110:113]
	v_mfma_f32_16x16x32_bf16 v[102:105], v[146:149], v[208:211], v[102:105]
	v_mfma_f32_16x16x32_bf16 v[94:97], v[166:169], v[208:211], v[94:97]
	v_mfma_f32_16x16x32_bf16 v[86:89], v[146:149], v[216:219], v[86:89]
	v_mfma_f32_16x16x32_bf16 v[78:81], v[166:169], v[216:219], v[78:81]
	v_mfma_f32_16x16x32_bf16 v[126:129], v[156:159], v[196:199], v[126:129]
	v_mfma_f32_16x16x32_bf16 v[122:125], v[170:173], v[196:199], v[122:125]
	v_mfma_f32_16x16x32_bf16 v[118:121], v[156:159], v[204:207], v[118:121]
	v_mfma_f32_16x16x32_bf16 v[110:113], v[170:173], v[204:207], v[110:113]
	v_mfma_f32_16x16x32_bf16 v[102:105], v[156:159], v[212:215], v[102:105]
	v_mfma_f32_16x16x32_bf16 v[94:97], v[170:173], v[212:215], v[94:97]
	v_mfma_f32_16x16x32_bf16 v[86:89], v[156:159], v[220:223], v[86:89]
	v_mfma_f32_16x16x32_bf16 v[78:81], v[170:173], v[220:223], v[78:81]
	s_setprio 0
	s_setprio 1
	v_mfma_f32_16x16x32_bf16 v[114:117], v[174:177], v[192:195], v[114:117]
	v_mfma_f32_16x16x32_bf16 v[106:109], v[182:185], v[192:195], v[106:109]
	v_mfma_f32_16x16x32_bf16 v[98:101], v[174:177], v[200:203], v[98:101]
	v_mfma_f32_16x16x32_bf16 v[90:93], v[182:185], v[200:203], v[90:93]
	v_mfma_f32_16x16x32_bf16 v[82:85], v[174:177], v[208:211], v[82:85]
	v_mfma_f32_16x16x32_bf16 v[74:77], v[182:185], v[208:211], v[74:77]
	v_mfma_f32_16x16x32_bf16 v[70:73], v[174:177], v[216:219], v[70:73]
	v_mfma_f32_16x16x32_bf16 v[66:69], v[182:185], v[216:219], v[66:69]
	v_mfma_f32_16x16x32_bf16 v[114:117], v[178:181], v[196:199], v[114:117]
	v_mfma_f32_16x16x32_bf16 v[106:109], v[186:189], v[196:199], v[106:109]
	v_mfma_f32_16x16x32_bf16 v[98:101], v[178:181], v[204:207], v[98:101]
	v_mfma_f32_16x16x32_bf16 v[90:93], v[186:189], v[204:207], v[90:93]
	v_mfma_f32_16x16x32_bf16 v[82:85], v[178:181], v[212:215], v[82:85]
	v_mfma_f32_16x16x32_bf16 v[74:77], v[186:189], v[212:215], v[74:77]
	v_mfma_f32_16x16x32_bf16 v[70:73], v[178:181], v[220:223], v[70:73]
	v_mfma_f32_16x16x32_bf16 v[66:69], v[186:189], v[220:223], v[66:69]
	s_setprio 0
	s_barrier
; #define PG8_STAGE(bufoff, gbase, voff) do { if constexpr (DIAG >= 1) break; _Pragma("unroll") for (int _i = 0; _i < 2; ++_i) \
;         __builtin_amdgcn_global_load_lds((const unsigned*)((const char*)(gbase) + (voff)[_i]), (PG8_LAS unsigned*)(lds + (bufoff) + ldsw + _i * 8192), 16, 0, 0); } while (0)
; #define PG8_LDA(dst, b, h) do { if constexpr (DIAG == 2 || DIAG == 3) break; _Pragma("unroll") for (int m = 0; m < 4; ++m) _Pragma("unroll") for (int k = 0; k < 2; ++k) dst[m][k] = *(const PG8_LAS bf16x8*)(lds + PG8_SA(b, h) + aoff + m * 2048 + k * 1024); } while (0)
; #define PG8_WAIT_V(n) asm volatile("s_waitcnt vmcnt(" #n ")" ::: "memory")
; #define PG8_WAIT_L(n) asm volatile("s_waitcnt lgkmcnt(" #n ")" ::: "memory")
; #define PG8_BAR __builtin_amdgcn_s_barrier()
; #define PG8_LP_OFF __builtin_amdgcn_s_setprio(0)
;     ...
;         for (int t = kb; t < ke; t += 2) {
;             const bool last = (t == ke - 2);
;             const char* a1 = cA + (size_t)(t + 1) * kstep;
;             const char* a2 = last ? nA : cA + (size_t)(t + 2) * kstep; const char* b2 = last ? nB : cB + (size_t)(t + 2) * kstep;
;             const char* a3 = a2 + kstep; const char* b3 = b2 + kstep;
;             if (last && has_next) S.a_ready(nxt);
;             if constexpr (SP2) {
;             PG8_LP_ON; PG8_LDB(B0, 0, 0); PG8_LDB(B1, 0, 1); PG8_SCHED; PG8_LDA(At, 0, 0); PG8_STAGE(PG8_SA(1, 1), a1 + hstep, voffA);
;             PG8_LP_OFF; PG8_WAIT_V(8); PG8_WAIT_L(0); PG8_BAR; PG8_MMA(0, 0, At, B0); PG8_MMA(0, 1, At, B1); PG8_BAR; PG8_SCHED;
;             PG8_LP_ON; PG8_LDA(At, 0, 1); PG8_STAGE(PG8_SB(0, 0), b2, voffB); PG8_STAGE(PG8_SB(0, 1), b2 + hstep, voffB); PG8_STAGE(PG8_SA(0, 0), a2, voffA);
;             PG8_LP_OFF; PG8_WAIT_V(8); PG8_WAIT_L(0); PG8_BAR; PG8_MMA(1, 0, At, B0); PG8_MMA(1, 1, At, B1); PG8_BAR; PG8_SCHED;
;             PG8_LP_ON; PG8_LDB(B0, 1, 0); PG8_LDB(B1, 1, 1); PG8_SCHED; PG8_LDA(At, 1, 0); PG8_STAGE(PG8_SA(0, 1), a2 + hstep, voffA);
;             PG8_LP_OFF; PG8_WAIT_V(8); PG8_WAIT_L(0); PG8_BAR; PG8_MMA(0, 0, At, B0); PG8_MMA(0, 1, At, B1); PG8_BAR; PG8_SCHED;
;             PG8_LP_ON; PG8_LDA(At, 1, 1); PG8_STAGE(PG8_SB(1, 0), b3, voffB); PG8_STAGE(PG8_SB(1, 1), b3 + hstep, voffB); PG8_STAGE(PG8_SA(1, 0), a3, voffA);
;             PG8_LP_OFF; PG8_WAIT_V(8); PG8_WAIT_L(0); PG8_BAR; PG8_MMA(1, 0, At, B0); PG8_MMA(1, 1, At, B1); PG8_BAR; PG8_SCHED;
	s_add_i32 s76, s92, s27
	v_lshl_add_u64 v[160:161], v[160:161], 0, s[10:11]
	s_mov_b32 m0, s76
	ds_read_b128 v[192:195], v155 offset:49152
	ds_read_b128 v[196:199], v155 offset:50176
	ds_read_b128 v[200:203], v155 offset:51200
	ds_read_b128 v[204:207], v155 offset:52224
	ds_read_b128 v[208:211], v155 offset:53248
	ds_read_b128 v[212:215], v155 offset:54272
	ds_read_b128 v[216:219], v155 offset:55296
	ds_read_b128 v[220:223], v155 offset:56320
	global_load_lds_dwordx4 v[160:161], off
	s_add_i32 m0, s76, 0x2000
	s_add_u32 s74, s74, 0x100080
	v_lshl_add_u64 v[160:161], v[224:225], 0, s[10:11]
	s_addc_u32 s75, s75, 0
	s_add_i32 s76, s93, s27
	global_load_lds_dwordx4 v[160:161], off
	v_lshl_add_u64 v[160:161], s[74:75], 0, v[132:133]
	s_mov_b32 m0, s76
	s_nop 0
	global_load_lds_dwordx4 v[160:161], off
	v_lshl_add_u64 v[160:161], s[74:75], 0, v[136:137]
	s_add_i32 m0, s76, 0x2000
	s_nop 0
	global_load_lds_dwordx4 v[160:161], off
	v_lshl_add_u64 v[160:161], v[226:227], 0, s[10:11]
	s_mov_b32 m0, s86
	s_nop 0
	global_load_lds_dwordx4 v[160:161], off
	v_lshl_add_u64 v[160:161], v[228:229], 0, s[10:11]
	s_mov_b32 m0, s87
	s_nop 0
	global_load_lds_dwordx4 v[160:161], off
	s_waitcnt vmcnt(8)
	s_barrier
	s_setprio 1
	s_waitcnt lgkmcnt(0)
	v_mfma_f32_16x16x32_bf16 v[62:65], v[146:149], v[192:195], v[62:65]
	v_mfma_f32_16x16x32_bf16 v[58:61], v[166:169], v[192:195], v[58:61]
	v_mfma_f32_16x16x32_bf16 v[54:57], v[146:149], v[200:203], v[54:57]
	v_mfma_f32_16x16x32_bf16 v[46:49], v[166:169], v[200:203], v[46:49]
	v_mfma_f32_16x16x32_bf16 v[38:41], v[146:149], v[208:211], v[38:41]
	v_mfma_f32_16x16x32_bf16 v[30:33], v[166:169], v[208:211], v[30:33]
	v_mfma_f32_16x16x32_bf16 v[22:25], v[146:149], v[216:219], v[22:25]
	v_mfma_f32_16x16x32_bf16 v[14:17], v[166:169], v[216:219], v[14:17]
	v_mfma_f32_16x16x32_bf16 v[62:65], v[156:159], v[196:199], v[62:65]
	v_mfma_f32_16x16x32_bf16 v[58:61], v[170:173], v[196:199], v[58:61]
	v_mfma_f32_16x16x32_bf16 v[54:57], v[156:159], v[204:207], v[54:57]
	v_mfma_f32_16x16x32_bf16 v[46:49], v[170:173], v[204:207], v[46:49]
	v_mfma_f32_16x16x32_bf16 v[38:41], v[156:159], v[212:215], v[38:41]
	v_mfma_f32_16x16x32_bf16 v[30:33], v[170:173], v[212:215], v[30:33]
	v_mfma_f32_16x16x32_bf16 v[22:25], v[156:159], v[220:223], v[22:25]
	v_mfma_f32_16x16x32_bf16 v[14:17], v[170:173], v[220:223], v[14:17]
	s_setprio 0
	s_setprio 1
	v_mfma_f32_16x16x32_bf16 v[50:53], v[174:177], v[192:195], v[50:53]
	v_mfma_f32_16x16x32_bf16 v[42:45], v[182:185], v[192:195], v[42:45]
	v_mfma_f32_16x16x32_bf16 v[34:37], v[174:177], v[200:203], v[34:37]
	v_mfma_f32_16x16x32_bf16 v[26:29], v[182:185], v[200:203], v[26:29]
	v_mfma_f32_16x16x32_bf16 v[18:21], v[174:177], v[208:211], v[18:21]
	v_mfma_f32_16x16x32_bf16 v[10:13], v[182:185], v[208:211], v[10:13]
	v_mfma_f32_16x16x32_bf16 v[6:9], v[174:177], v[216:219], v[6:9]
	v_mfma_f32_16x16x32_bf16 v[2:5], v[182:185], v[216:219], v[2:5]
	v_mfma_f32_16x16x32_bf16 v[50:53], v[178:181], v[196:199], v[50:53]
	v_mfma_f32_16x16x32_bf16 v[42:45], v[186:189], v[196:199], v[42:45]
	v_mfma_f32_16x16x32_bf16 v[34:37], v[178:181], v[204:207], v[34:37]
	v_mfma_f32_16x16x32_bf16 v[26:29], v[186:189], v[204:207], v[26:29]
	v_mfma_f32_16x16x32_bf16 v[18:21], v[178:181], v[212:215], v[18:21]
	v_mfma_f32_16x16x32_bf16 v[10:13], v[186:189], v[212:215], v[10:13]
	v_mfma_f32_16x16x32_bf16 v[6:9], v[178:181], v[220:223], v[6:9]
	v_mfma_f32_16x16x32_bf16 v[2:5], v[186:189], v[220:223], v[2:5]
	s_setprio 0
	s_barrier
	s_add_i32 s91, s91, 2
	s_add_u32 s72, s72, 0x100
	s_addc_u32 s73, s73, 0
	s_add_u32 s82, s82, 0x100
	s_addc_u32 s83, s83, 0
	s_cmp_gt_u32 s91, 61
	s_cbranch_scc0 .LBB0_521
	s_and_b64 vcc, exec, s[12:13]
	s_cbranch_vccz .LBB0_524
	s_barrier

; #define PG8_STAGE(bufoff, gbase, voff) do { if constexpr (DIAG >= 1) break; _Pragma("unroll") for (int _i = 0; _i < 2; ++_i) \
;         __builtin_amdgcn_global_load_lds((const unsigned*)((const char*)(gbase) + (voff)[_i]), (PG8_LAS unsigned*)(lds + (bufoff) + ldsw + _i * 8192), 16, 0, 0); } while (0)
; #define PG8_LDA(dst, b, h) do { if constexpr (DIAG == 2 || DIAG == 3) break; _Pragma("unroll") for (int m = 0; m < 4; ++m) _Pragma("unroll") for (int k = 0; k < 2; ++k) dst[m][k] = *(const PG8_LAS bf16x8*)(lds + PG8_SA(b, h) + aoff + m * 2048 + k * 1024); } while (0)
; #define PG8_LDB(dst, b, h) do { if constexpr (DIAG == 2 || DIAG == 3) break; _Pragma("unroll") for (int n = 0; n < 2; ++n) _Pragma("unroll") for (int k = 0; k < 2; ++k) dst[n][k] = *(const PG8_LAS bf16x8*)(lds + PG8_SB(b, h) + boff + n * 2048 + k * 1024); } while (0)
; #define PG8_WAIT_V(n) asm volatile("s_waitcnt vmcnt(" #n ")" ::: "memory")
; #define PG8_WAIT_L(n) asm volatile("s_waitcnt lgkmcnt(" #n ")" ::: "memory")
; #define PG8_BAR __builtin_amdgcn_s_barrier()
; #define PG8_LP_ON __builtin_amdgcn_s_setprio(PG8_LOADPRIO)
; #define PG8_LP_OFF __builtin_amdgcn_s_setprio(0)
; #define PG8_LP_ON do {} while (0)
; #define PG8_LP_OFF do {} while (0)
; #define PG8_SCHED __builtin_amdgcn_sched_barrier(0)
;     ...
;         for (int t = kb; t < ke; t += 2) {
;             const bool last = (t == ke - 2);
;             const char* a1 = cA + (size_t)(t + 1) * kstep;
;             const char* a2 = last ? nA : cA + (size_t)(t + 2) * kstep; const char* b2 = last ? nB : cB + (size_t)(t + 2) * kstep;
;             const char* a3 = a2 + kstep; const char* b3 = b2 + kstep;
;             if (last && has_next) S.a_ready(nxt);
;             if constexpr (SP2) {
;             PG8_LP_ON; PG8_LDB(B0, 0, 0); PG8_LDB(B1, 0, 1); PG8_SCHED; PG8_LDA(At, 0, 0); PG8_STAGE(PG8_SA(1, 1), a1 + hstep, voffA);
;             PG8_LP_OFF; PG8_WAIT_V(8); PG8_WAIT_L(0); PG8_BAR; PG8_MMA(0, 0, At, B0); PG8_MMA(0, 1, At, B1); PG8_BAR; PG8_SCHED;
;             PG8_LP_ON; PG8_LDA(At, 0, 1); PG8_STAGE(PG8_SB(0, 0), b2, voffB); PG8_STAGE(PG8_SB(0, 1), b2 + hstep, voffB); PG8_STAGE(PG8_SA(0, 0), a2, voffA);
;             PG8_LP_OFF; PG8_WAIT_V(8); PG8_WAIT_L(0); PG8_BAR; PG8_MMA(1, 0, At, B0); PG8_MMA(1, 1, At, B1); PG8_BAR; PG8_SCHED;
.LBB0_725:
	ds_read_b128 v[130:133], v177
	ds_read_b128 v[134:137], v177 offset:1024
	ds_read_b128 v[138:141], v177 offset:2048
	ds_read_b128 v[142:145], v177 offset:3072
	ds_read_b128 v[166:169], v178
	ds_read_b128 v[170:173], v178 offset:1024
	ds_read_b128 v[180:183], v178 offset:2048
	ds_read_b128 v[184:187], v178 offset:3072
	s_add_u32 s62, s60, 0xfff00080
	s_addc_u32 s63, s61, -1
	s_cmp_eq_u32 s83, 60
	s_cselect_b32 s65, s5, s63
	s_cselect_b32 s64, s26, s62
	s_cselect_b32 s63, s23, s82
	s_cselect_b32 s62, s27, s47
	v_lshl_add_u64 v[160:161], s[60:61], 0, v[152:153]
	s_add_i32 m0, s1, 0xc000
	ds_read_b128 v[188:191], v179
	ds_read_b128 v[192:195], v179 offset:1024
	ds_read_b128 v[196:199], v179 offset:2048
	ds_read_b128 v[200:203], v179 offset:3072
	ds_read_b128 v[204:207], v179 offset:4096
	ds_read_b128 v[208:211], v179 offset:5120
	ds_read_b128 v[212:215], v179 offset:6144
	ds_read_b128 v[216:219], v179 offset:7168
	global_load_lds_dwordx4 v[160:161], off
	v_lshl_add_u64 v[160:161], s[60:61], 0, v[154:155]
	s_add_i32 m0, s1, 0xe000
	s_nop 0
	global_load_lds_dwordx4 v[160:161], off
	s_waitcnt vmcnt(8)
	s_barrier
	s_setprio 1
	s_waitcnt lgkmcnt(0)
	v_mfma_f32_16x16x32_bf16 v[126:129], v[130:133], v[188:191], v[126:129]
	v_mfma_f32_16x16x32_bf16 v[122:125], v[138:141], v[188:191], v[122:125]
	v_mfma_f32_16x16x32_bf16 v[110:113], v[130:133], v[196:199], v[110:113]
	v_mfma_f32_16x16x32_bf16 v[106:109], v[138:141], v[196:199], v[106:109]
	v_mfma_f32_16x16x32_bf16 v[94:97], v[130:133], v[204:207], v[94:97]
	v_mfma_f32_16x16x32_bf16 v[90:93], v[138:141], v[204:207], v[90:93]
	v_mfma_f32_16x16x32_bf16 v[78:81], v[130:133], v[212:215], v[78:81]
	v_mfma_f32_16x16x32_bf16 v[74:77], v[138:141], v[212:215], v[74:77]
	v_mfma_f32_16x16x32_bf16 v[126:129], v[134:137], v[192:195], v[126:129]
	v_mfma_f32_16x16x32_bf16 v[122:125], v[142:145], v[192:195], v[122:125]
	v_mfma_f32_16x16x32_bf16 v[110:113], v[134:137], v[200:203], v[110:113]
	v_mfma_f32_16x16x32_bf16 v[106:109], v[142:145], v[200:203], v[106:109]
	v_mfma_f32_16x16x32_bf16 v[94:97], v[134:137], v[208:211], v[94:97]
	v_mfma_f32_16x16x32_bf16 v[90:93], v[142:145], v[208:211], v[90:93]
	v_mfma_f32_16x16x32_bf16 v[78:81], v[134:137], v[216:219], v[78:81]
	v_mfma_f32_16x16x32_bf16 v[74:77], v[142:145], v[216:219], v[74:77]
	s_setprio 0
	s_setprio 1
	v_mfma_f32_16x16x32_bf16 v[118:121], v[166:169], v[188:191], v[118:121]
	v_mfma_f32_16x16x32_bf16 v[114:117], v[180:183], v[188:191], v[114:117]
	v_mfma_f32_16x16x32_bf16 v[102:105], v[166:169], v[196:199], v[102:105]
	v_mfma_f32_16x16x32_bf16 v[98:101], v[180:183], v[196:199], v[98:101]
	v_mfma_f32_16x16x32_bf16 v[86:89], v[166:169], v[204:207], v[86:89]
	v_mfma_f32_16x16x32_bf16 v[82:85], v[180:183], v[204:207], v[82:85]
	v_mfma_f32_16x16x32_bf16 v[70:73], v[166:169], v[212:215], v[70:73]
	v_mfma_f32_16x16x32_bf16 v[66:69], v[180:183], v[212:215], v[66:69]
	v_mfma_f32_16x16x32_bf16 v[118:121], v[170:173], v[192:195], v[118:121]
	v_mfma_f32_16x16x32_bf16 v[114:117], v[184:187], v[192:195], v[114:117]
	v_mfma_f32_16x16x32_bf16 v[102:105], v[170:173], v[200:203], v[102:105]
	v_mfma_f32_16x16x32_bf16 v[98:101], v[184:187], v[200:203], v[98:101]
	v_mfma_f32_16x16x32_bf16 v[86:89], v[170:173], v[208:211], v[86:89]
	v_mfma_f32_16x16x32_bf16 v[82:85], v[184:187], v[208:211], v[82:85]
	v_mfma_f32_16x16x32_bf16 v[70:73], v[170:173], v[216:219], v[70:73]
	v_mfma_f32_16x16x32_bf16 v[66:69], v[184:187], v[216:219], v[66:69]
	s_setprio 0
	s_barrier
	s_add_i32 s84, s78, s0
	v_lshl_add_u64 v[160:161], s[62:63], 0, v[146:147]
	s_mov_b32 m0, s84
	ds_read_b128 v[188:191], v179 offset:16384
	ds_read_b128 v[192:195], v179 offset:17408
	ds_read_b128 v[196:199], v179 offset:18432
	ds_read_b128 v[200:203], v179 offset:19456
	ds_read_b128 v[204:207], v179 offset:20480
	ds_read_b128 v[208:211], v179 offset:21504
	ds_read_b128 v[212:215], v179 offset:22528
	ds_read_b128 v[216:219], v179 offset:23552
	global_load_lds_dwordx4 v[160:161], off
	s_add_i32 m0, s84, 0x2000
	s_add_u32 s84, s62, 0x100000
	v_lshl_add_u64 v[174:175], s[62:63], 0, v[148:149]
	s_addc_u32 s85, s63, 0
	s_add_i32 s86, s79, s0
	global_load_lds_dwordx4 v[174:175], off
	v_lshl_add_u64 v[220:221], s[84:85], 0, v[146:147]
	s_mov_b32 m0, s86
	v_lshl_add_u64 v[222:223], s[64:65], 0, v[148:149]
	global_load_lds_dwordx4 v[220:221], off
	v_lshl_add_u64 v[220:221], s[84:85], 0, v[148:149]
	s_add_i32 m0, s86, 0x2000
	s_nop 0
	global_load_lds_dwordx4 v[220:221], off
	v_lshl_add_u64 v[220:221], s[64:65], 0, v[146:147]
	s_mov_b32 m0, s1
	s_nop 0
	global_load_lds_dwordx4 v[220:221], off
	s_mov_b32 m0, s34
	s_nop 0
	global_load_lds_dwordx4 v[222:223], off
	s_waitcnt vmcnt(8)
	s_barrier
; #define PG8_STAGE(bufoff, gbase, voff) do { if constexpr (DIAG >= 1) break; _Pragma("unroll") for (int _i = 0; _i < 2; ++_i) \
;         __builtin_amdgcn_global_load_lds((const unsigned*)((const char*)(gbase) + (voff)[_i]), (PG8_LAS unsigned*)(lds + (bufoff) + ldsw + _i * 8192), 16, 0, 0); } while (0)
; #define PG8_LDA(dst, b, h) do { if constexpr (DIAG == 2 || DIAG == 3) break; _Pragma("unroll") for (int m = 0; m < 4; ++m) _Pragma("unroll") for (int k = 0; k < 2; ++k) dst[m][k] = *(const PG8_LAS bf16x8*)(lds + PG8_SA(b, h) + aoff + m * 2048 + k * 1024); } while (0)
; #define PG8_LDB(dst, b, h) do { if constexpr (DIAG == 2 || DIAG == 3) break; _Pragma("unroll") for (int n = 0; n < 2; ++n) _Pragma("unroll") for (int k = 0; k < 2; ++k) dst[n][k] = *(const PG8_LAS bf16x8*)(lds + PG8_SB(b, h) + boff + n * 2048 + k * 1024); } while (0)
; #define PG8_WAIT_V(n) asm volatile("s_waitcnt vmcnt(" #n ")" ::: "memory")
; #define PG8_WAIT_L(n) asm volatile("s_waitcnt lgkmcnt(" #n ")" ::: "memory")
; #define PG8_BAR __builtin_amdgcn_s_barrier()
; #define PG8_LP_ON __builtin_amdgcn_s_setprio(PG8_LOADPRIO)
; #define PG8_LP_OFF __builtin_amdgcn_s_setprio(0)
; #define PG8_LP_ON do {} while (0)
; #define PG8_LP_OFF do {} while (0)
; #define PG8_SCHED __builtin_amdgcn_sched_barrier(0)
;     ...
;             PG8_LP_OFF; PG8_WAIT_V(8); PG8_WAIT_L(0); PG8_BAR; PG8_MMA(1, 0, At, B0); PG8_MMA(1, 1, At, B1); PG8_BAR; PG8_SCHED;
;             PG8_LP_ON; PG8_LDB(B0, 1, 0); PG8_LDB(B1, 1, 1); PG8_SCHED; PG8_LDA(At, 1, 0); PG8_STAGE(PG8_SA(0, 1), a2 + hstep, voffA);
;             PG8_LP_OFF; PG8_WAIT_V(8); PG8_WAIT_L(0); PG8_BAR; PG8_MMA(0, 0, At, B0); PG8_MMA(0, 1, At, B1); PG8_BAR; PG8_SCHED;
	s_setprio 1
	s_waitcnt lgkmcnt(0)
	v_mfma_f32_16x16x32_bf16 v[62:65], v[130:133], v[188:191], v[62:65]
	v_mfma_f32_16x16x32_bf16 v[58:61], v[138:141], v[188:191], v[58:61]
	v_mfma_f32_16x16x32_bf16 v[46:49], v[130:133], v[196:199], v[46:49]
	v_mfma_f32_16x16x32_bf16 v[42:45], v[138:141], v[196:199], v[42:45]
	v_mfma_f32_16x16x32_bf16 v[30:33], v[130:133], v[204:207], v[30:33]
	v_mfma_f32_16x16x32_bf16 v[26:29], v[138:141], v[204:207], v[26:29]
	v_mfma_f32_16x16x32_bf16 v[14:17], v[130:133], v[212:215], v[14:17]
	v_mfma_f32_16x16x32_bf16 v[10:13], v[138:141], v[212:215], v[10:13]
	v_mfma_f32_16x16x32_bf16 v[62:65], v[134:137], v[192:195], v[62:65]
	v_mfma_f32_16x16x32_bf16 v[58:61], v[142:145], v[192:195], v[58:61]
	v_mfma_f32_16x16x32_bf16 v[46:49], v[134:137], v[200:203], v[46:49]
	v_mfma_f32_16x16x32_bf16 v[42:45], v[142:145], v[200:203], v[42:45]
	v_mfma_f32_16x16x32_bf16 v[30:33], v[134:137], v[208:211], v[30:33]
	v_mfma_f32_16x16x32_bf16 v[26:29], v[142:145], v[208:211], v[26:29]
	v_mfma_f32_16x16x32_bf16 v[14:17], v[134:137], v[216:219], v[14:17]
	v_mfma_f32_16x16x32_bf16 v[10:13], v[142:145], v[216:219], v[10:13]
	s_setprio 0
	s_setprio 1
	v_mfma_f32_16x16x32_bf16 v[54:57], v[166:169], v[188:191], v[54:57]
	v_mfma_f32_16x16x32_bf16 v[50:53], v[180:183], v[188:191], v[50:53]
	v_mfma_f32_16x16x32_bf16 v[38:41], v[166:169], v[196:199], v[38:41]
	v_mfma_f32_16x16x32_bf16 v[34:37], v[180:183], v[196:199], v[34:37]
	v_mfma_f32_16x16x32_bf16 v[22:25], v[166:169], v[204:207], v[22:25]
	v_mfma_f32_16x16x32_bf16 v[18:21], v[180:183], v[204:207], v[18:21]
	v_mfma_f32_16x16x32_bf16 v[6:9], v[166:169], v[212:215], v[6:9]
	v_mfma_f32_16x16x32_bf16 v[2:5], v[180:183], v[212:215], v[2:5]
	v_mfma_f32_16x16x32_bf16 v[54:57], v[170:173], v[192:195], v[54:57]
	v_mfma_f32_16x16x32_bf16 v[50:53], v[184:187], v[192:195], v[50:53]
	v_mfma_f32_16x16x32_bf16 v[38:41], v[170:173], v[200:203], v[38:41]
	v_mfma_f32_16x16x32_bf16 v[34:37], v[184:187], v[200:203], v[34:37]
	v_mfma_f32_16x16x32_bf16 v[22:25], v[170:173], v[208:211], v[22:25]
	v_mfma_f32_16x16x32_bf16 v[18:21], v[184:187], v[208:211], v[18:21]
	v_mfma_f32_16x16x32_bf16 v[6:9], v[170:173], v[216:219], v[6:9]
	v_mfma_f32_16x16x32_bf16 v[2:5], v[184:187], v[216:219], v[2:5]
	s_setprio 0
	s_barrier
	s_add_i32 s84, 0, 0x18000
	s_add_i32 s85, 0, 0x1c000
	v_add_u32_e32 v142, s84, v165
	v_add_u32_e32 v150, s85, v165
	ds_read_b128 v[130:133], v142
	ds_read_b128 v[134:137], v142 offset:1024
	ds_read_b128 v[138:141], v142 offset:2048
	ds_read_b128 v[142:145], v142 offset:3072
	ds_read_b128 v[166:169], v150
	ds_read_b128 v[170:173], v150 offset:1024
	ds_read_b128 v[180:183], v150 offset:2048
	ds_read_b128 v[184:187], v150 offset:3072
	s_add_u32 s64, s64, 0x100000
	s_addc_u32 s65, s65, 0
	s_mov_b32 m0, s55
	v_lshl_add_u64 v[224:225], s[64:65], 0, v[146:147]
	ds_read_b128 v[188:191], v179 offset:32768
	ds_read_b128 v[192:195], v179 offset:33792
	ds_read_b128 v[196:199], v179 offset:34816
	ds_read_b128 v[200:203], v179 offset:35840
	ds_read_b128 v[204:207], v179 offset:36864
	ds_read_b128 v[208:211], v179 offset:37888
	ds_read_b128 v[212:215], v179 offset:38912
	ds_read_b128 v[216:219], v179 offset:39936
	global_load_lds_dwordx4 v[224:225], off
	v_lshl_add_u64 v[224:225], s[64:65], 0, v[148:149]
	s_mov_b32 m0, s66
	s_nop 0
	global_load_lds_dwordx4 v[224:225], off
	s_waitcnt vmcnt(8)
	s_barrier
	s_setprio 1
	s_waitcnt lgkmcnt(0)
	v_mfma_f32_16x16x32_bf16 v[126:129], v[130:133], v[188:191], v[126:129]
	v_mfma_f32_16x16x32_bf16 v[122:125], v[138:141], v[188:191], v[122:125]
	v_mfma_f32_16x16x32_bf16 v[110:113], v[130:133], v[196:199], v[110:113]
	v_mfma_f32_16x16x32_bf16 v[106:109], v[138:141], v[196:199], v[106:109]
	v_mfma_f32_16x16x32_bf16 v[94:97], v[130:133], v[204:207], v[94:97]
	v_mfma_f32_16x16x32_bf16 v[90:93], v[138:141], v[204:207], v[90:93]
	v_mfma_f32_16x16x32_bf16 v[78:81], v[130:133], v[212:215], v[78:81]
	v_mfma_f32_16x16x32_bf16 v[74:77], v[138:141], v[212:215], v[74:77]
	v_mfma_f32_16x16x32_bf16 v[126:129], v[134:137], v[192:195], v[126:129]
	v_mfma_f32_16x16x32_bf16 v[122:125], v[142:145], v[192:195], v[122:125]
	v_mfma_f32_16x16x32_bf16 v[110:113], v[134:137], v[200:203], v[110:113]
	v_mfma_f32_16x16x32_bf16 v[106:109], v[142:145], v[200:203], v[106:109]
	v_mfma_f32_16x16x32_bf16 v[94:97], v[134:137], v[208:211], v[94:97]
	v_mfma_f32_16x16x32_bf16 v[90:93], v[142:145], v[208:211], v[90:93]
	v_mfma_f32_16x16x32_bf16 v[78:81], v[134:137], v[216:219], v[78:81]
	v_mfma_f32_16x16x32_bf16 v[74:77], v[142:145], v[216:219], v[74:77]
	s_setprio 0
	s_setprio 1
	v_mfma_f32_16x16x32_bf16 v[118:121], v[166:169], v[188:191], v[118:121]
	v_mfma_f32_16x16x32_bf16 v[114:117], v[180:183], v[188:191], v[114:117]
	v_mfma_f32_16x16x32_bf16 v[102:105], v[166:169], v[196:199], v[102:105]
	v_mfma_f32_16x16x32_bf16 v[98:101], v[180:183], v[196:199], v[98:101]
	v_mfma_f32_16x16x32_bf16 v[86:89], v[166:169], v[204:207], v[86:89]
	v_mfma_f32_16x16x32_bf16 v[82:85], v[180:183], v[204:207], v[82:85]
	v_mfma_f32_16x16x32_bf16 v[70:73], v[166:169], v[212:215], v[70:73]
	v_mfma_f32_16x16x32_bf16 v[66:69], v[180:183], v[212:215], v[66:69]
	v_mfma_f32_16x16x32_bf16 v[118:121], v[170:173], v[192:195], v[118:121]
	v_mfma_f32_16x16x32_bf16 v[114:117], v[184:187], v[192:195], v[114:117]
	v_mfma_f32_16x16x32_bf16 v[102:105], v[170:173], v[200:203], v[102:105]
	v_mfma_f32_16x16x32_bf16 v[98:101], v[184:187], v[200:203], v[98:101]
	v_mfma_f32_16x16x32_bf16 v[86:89], v[170:173], v[208:211], v[86:89]
	v_mfma_f32_16x16x32_bf16 v[82:85], v[184:187], v[208:211], v[82:85]
	v_mfma_f32_16x16x32_bf16 v[70:73], v[170:173], v[216:219], v[70:73]
	v_mfma_f32_16x16x32_bf16 v[66:69], v[184:187], v[216:219], v[66:69]
	s_setprio 0
	s_barrier
; #define PG8_STAGE(bufoff, gbase, voff) do { if constexpr (DIAG >= 1) break; _Pragma("unroll") for (int _i = 0; _i < 2; ++_i) \
;         __builtin_amdgcn_global_load_lds((const unsigned*)((const char*)(gbase) + (voff)[_i]), (PG8_LAS unsigned*)(lds + (bufoff) + ldsw + _i * 8192), 16, 0, 0); } while (0)
; #define PG8_LDA(dst, b, h) do { if constexpr (DIAG == 2 || DIAG == 3) break; _Pragma("unroll") for (int m = 0; m < 4; ++m) _Pragma("unroll") for (int k = 0; k < 2; ++k) dst[m][k] = *(const PG8_LAS bf16x8*)(lds + PG8_SA(b, h) + aoff + m * 2048 + k * 1024); } while (0)
; #define PG8_WAIT_V(n) asm volatile("s_waitcnt vmcnt(" #n ")" ::: "memory")
; #define PG8_WAIT_L(n) asm volatile("s_waitcnt lgkmcnt(" #n ")" ::: "memory")
; #define PG8_BAR __builtin_amdgcn_s_barrier()
; #define PG8_LP_OFF __builtin_amdgcn_s_setprio(0)
;     ...
;         for (int t = kb; t < ke; t += 2) {
;             const bool last = (t == ke - 2);
;             const char* a1 = cA + (size_t)(t + 1) * kstep;
;             const char* a2 = last ? nA : cA + (size_t)(t + 2) * kstep; const char* b2 = last ? nB : cB + (size_t)(t + 2) * kstep;
;             const char* a3 = a2 + kstep; const char* b3 = b2 + kstep;
;             if (last && has_next) S.a_ready(nxt);
;             if constexpr (SP2) {
;             PG8_LP_ON; PG8_LDB(B0, 0, 0); PG8_LDB(B1, 0, 1); PG8_SCHED; PG8_LDA(At, 0, 0); PG8_STAGE(PG8_SA(1, 1), a1 + hstep, voffA);
;             PG8_LP_OFF; PG8_WAIT_V(8); PG8_WAIT_L(0); PG8_BAR; PG8_MMA(0, 0, At, B0); PG8_MMA(0, 1, At, B1); PG8_BAR; PG8_SCHED;
;             PG8_LP_ON; PG8_LDA(At, 0, 1); PG8_STAGE(PG8_SB(0, 0), b2, voffB); PG8_STAGE(PG8_SB(0, 1), b2 + hstep, voffB); PG8_STAGE(PG8_SA(0, 0), a2, voffA);
;             PG8_LP_OFF; PG8_WAIT_V(8); PG8_WAIT_L(0); PG8_BAR; PG8_MMA(1, 0, At, B0); PG8_MMA(1, 1, At, B1); PG8_BAR; PG8_SCHED;
;             PG8_LP_ON; PG8_LDB(B0, 1, 0); PG8_LDB(B1, 1, 1); PG8_SCHED; PG8_LDA(At, 1, 0); PG8_STAGE(PG8_SA(0, 1), a2 + hstep, voffA);
;             PG8_LP_OFF; PG8_WAIT_V(8); PG8_WAIT_L(0); PG8_BAR; PG8_MMA(0, 0, At, B0); PG8_MMA(0, 1, At, B1); PG8_BAR; PG8_SCHED;
;             PG8_LP_ON; PG8_LDA(At, 1, 1); PG8_STAGE(PG8_SB(1, 0), b3, voffB); PG8_STAGE(PG8_SB(1, 1), b3 + hstep, voffB); PG8_STAGE(PG8_SA(1, 0), a3, voffA);
;             PG8_LP_OFF; PG8_WAIT_V(8); PG8_WAIT_L(0); PG8_BAR; PG8_MMA(1, 0, At, B0); PG8_MMA(1, 1, At, B1); PG8_BAR; PG8_SCHED;
	s_add_i32 s64, s84, s0
	v_lshl_add_u64 v[160:161], v[160:161], 0, s[14:15]
	s_mov_b32 m0, s64
	ds_read_b128 v[188:191], v179 offset:49152
	ds_read_b128 v[192:195], v179 offset:50176
	ds_read_b128 v[196:199], v179 offset:51200
	ds_read_b128 v[200:203], v179 offset:52224
	ds_read_b128 v[204:207], v179 offset:53248
	ds_read_b128 v[208:211], v179 offset:54272
	ds_read_b128 v[212:215], v179 offset:55296
	ds_read_b128 v[216:219], v179 offset:56320
	global_load_lds_dwordx4 v[160:161], off
	s_add_i32 m0, s64, 0x2000
	s_add_u32 s62, s62, 0x100080
	v_lshl_add_u64 v[160:161], v[174:175], 0, s[14:15]
	s_addc_u32 s63, s63, 0
	s_add_i32 s64, s85, s0
	global_load_lds_dwordx4 v[160:161], off
	v_lshl_add_u64 v[160:161], s[62:63], 0, v[146:147]
	s_mov_b32 m0, s64
	s_nop 0
	global_load_lds_dwordx4 v[160:161], off
	v_lshl_add_u64 v[160:161], s[62:63], 0, v[148:149]
	s_add_i32 m0, s64, 0x2000
	s_nop 0
	global_load_lds_dwordx4 v[160:161], off
	v_lshl_add_u64 v[160:161], v[220:221], 0, s[14:15]
	s_mov_b32 m0, s74
	s_nop 0
	global_load_lds_dwordx4 v[160:161], off
	v_lshl_add_u64 v[160:161], v[222:223], 0, s[14:15]
	s_mov_b32 m0, s75
	s_nop 0
	global_load_lds_dwordx4 v[160:161], off
	s_waitcnt vmcnt(8)
	s_barrier
	s_setprio 1
	s_waitcnt lgkmcnt(0)
	v_mfma_f32_16x16x32_bf16 v[62:65], v[130:133], v[188:191], v[62:65]
	v_mfma_f32_16x16x32_bf16 v[58:61], v[138:141], v[188:191], v[58:61]
	v_mfma_f32_16x16x32_bf16 v[46:49], v[130:133], v[196:199], v[46:49]
	v_mfma_f32_16x16x32_bf16 v[42:45], v[138:141], v[196:199], v[42:45]
	v_mfma_f32_16x16x32_bf16 v[30:33], v[130:133], v[204:207], v[30:33]
	v_mfma_f32_16x16x32_bf16 v[26:29], v[138:141], v[204:207], v[26:29]
	v_mfma_f32_16x16x32_bf16 v[14:17], v[130:133], v[212:215], v[14:17]
	v_mfma_f32_16x16x32_bf16 v[10:13], v[138:141], v[212:215], v[10:13]
	v_mfma_f32_16x16x32_bf16 v[62:65], v[134:137], v[192:195], v[62:65]
	v_mfma_f32_16x16x32_bf16 v[58:61], v[142:145], v[192:195], v[58:61]
	v_mfma_f32_16x16x32_bf16 v[46:49], v[134:137], v[200:203], v[46:49]
	v_mfma_f32_16x16x32_bf16 v[42:45], v[142:145], v[200:203], v[42:45]
	v_mfma_f32_16x16x32_bf16 v[30:33], v[134:137], v[208:211], v[30:33]
	v_mfma_f32_16x16x32_bf16 v[26:29], v[142:145], v[208:211], v[26:29]
	v_mfma_f32_16x16x32_bf16 v[14:17], v[134:137], v[216:219], v[14:17]
	v_mfma_f32_16x16x32_bf16 v[10:13], v[142:145], v[216:219], v[10:13]
	s_setprio 0
	s_setprio 1
	v_mfma_f32_16x16x32_bf16 v[54:57], v[166:169], v[188:191], v[54:57]
	v_mfma_f32_16x16x32_bf16 v[50:53], v[180:183], v[188:191], v[50:53]
	v_mfma_f32_16x16x32_bf16 v[38:41], v[166:169], v[196:199], v[38:41]
	v_mfma_f32_16x16x32_bf16 v[34:37], v[180:183], v[196:199], v[34:37]
	v_mfma_f32_16x16x32_bf16 v[22:25], v[166:169], v[204:207], v[22:25]
	v_mfma_f32_16x16x32_bf16 v[18:21], v[180:183], v[204:207], v[18:21]
	v_mfma_f32_16x16x32_bf16 v[6:9], v[166:169], v[212:215], v[6:9]
	v_mfma_f32_16x16x32_bf16 v[2:5], v[180:183], v[212:215], v[2:5]
	v_mfma_f32_16x16x32_bf16 v[54:57], v[170:173], v[192:195], v[54:57]
	v_mfma_f32_16x16x32_bf16 v[50:53], v[184:187], v[192:195], v[50:53]
	v_mfma_f32_16x16x32_bf16 v[38:41], v[170:173], v[200:203], v[38:41]
	v_mfma_f32_16x16x32_bf16 v[34:37], v[184:187], v[200:203], v[34:37]
	v_mfma_f32_16x16x32_bf16 v[22:25], v[170:173], v[208:211], v[22:25]
	v_mfma_f32_16x16x32_bf16 v[18:21], v[184:187], v[208:211], v[18:21]
	v_mfma_f32_16x16x32_bf16 v[6:9], v[170:173], v[216:219], v[6:9]
	v_mfma_f32_16x16x32_bf16 v[2:5], v[184:187], v[216:219], v[2:5]
	s_setprio 0
	s_barrier
	s_add_i32 s83, s83, 2
	s_add_u32 s60, s60, 0x100
	s_addc_u32 s61, s61, 0
	s_add_u32 s47, s47, 0x100
	s_addc_u32 s82, s82, 0
	s_cmp_gt_u32 s83, 61
	s_cbranch_scc0 .LBB0_725
	s_and_b64 vcc, exec, s[16:17]
	s_cbranch_vccz .LBB0_728
	s_barrier

; #define PG8_STAGE(bufoff, gbase, voff) do { if constexpr (DIAG >= 1) break; _Pragma("unroll") for (int _i = 0; _i < 2; ++_i) \
;         __builtin_amdgcn_global_load_lds((const unsigned*)((const char*)(gbase) + (voff)[_i]), (PG8_LAS unsigned*)(lds + (bufoff) + ldsw + _i * 8192), 16, 0, 0); } while (0)
; #define PG8_LDA(dst, b, h) do { if constexpr (DIAG == 2 || DIAG == 3) break; _Pragma("unroll") for (int m = 0; m < 4; ++m) _Pragma("unroll") for (int k = 0; k < 2; ++k) dst[m][k] = *(const PG8_LAS bf16x8*)(lds + PG8_SA(b, h) + aoff + m * 2048 + k * 1024); } while (0)
; #define PG8_LDB(dst, b, h) do { if constexpr (DIAG == 2 || DIAG == 3) break; _Pragma("unroll") for (int n = 0; n < 2; ++n) _Pragma("unroll") for (int k = 0; k < 2; ++k) dst[n][k] = *(const PG8_LAS bf16x8*)(lds + PG8_SB(b, h) + boff + n * 2048 + k * 1024); } while (0)
; #define PG8_WAIT_V(n) asm volatile("s_waitcnt vmcnt(" #n ")" ::: "memory")
; #define PG8_WAIT_L(n) asm volatile("s_waitcnt lgkmcnt(" #n ")" ::: "memory")
; #define PG8_BAR __builtin_amdgcn_s_barrier()
; #define PG8_LP_ON __builtin_amdgcn_s_setprio(PG8_LOADPRIO)
; #define PG8_LP_OFF __builtin_amdgcn_s_setprio(0)
; #define PG8_LP_ON do {} while (0)
; #define PG8_LP_OFF do {} while (0)
; #define PG8_SCHED __builtin_amdgcn_sched_barrier(0)
;     ...
;         for (int t = kb; t < ke; t += 2) {
;             const bool last = (t == ke - 2);
;             const char* a1 = cA + (size_t)(t + 1) * kstep;
;             const char* a2 = last ? nA : cA + (size_t)(t + 2) * kstep; const char* b2 = last ? nB : cB + (size_t)(t + 2) * kstep;
;             const char* a3 = a2 + kstep; const char* b3 = b2 + kstep;
;             if (last && has_next) S.a_ready(nxt);
;             if constexpr (SP2) {
;             PG8_LP_ON; PG8_LDB(B0, 0, 0); PG8_LDB(B1, 0, 1); PG8_SCHED; PG8_LDA(At, 0, 0); PG8_STAGE(PG8_SA(1, 1), a1 + hstep, voffA);
;             PG8_LP_OFF; PG8_WAIT_V(8); PG8_WAIT_L(0); PG8_BAR; PG8_MMA(0, 0, At, B0); PG8_MMA(0, 1, At, B1); PG8_BAR; PG8_SCHED;
;             PG8_LP_ON; PG8_LDA(At, 0, 1); PG8_STAGE(PG8_SB(0, 0), b2, voffB); PG8_STAGE(PG8_SB(0, 1), b2 + hstep, voffB); PG8_STAGE(PG8_SA(0, 0), a2, voffA);
;             PG8_LP_OFF; PG8_WAIT_V(8); PG8_WAIT_L(0); PG8_BAR; PG8_MMA(1, 0, At, B0); PG8_MMA(1, 1, At, B1); PG8_BAR; PG8_SCHED;
.LBB0_918:
	s_add_i32 s4, s55, 1
	s_ashr_i32 s5, s4, 31
	s_lshl_b64 s[90:91], s[4:5], 7
	s_add_i32 s4, s55, 2
	s_ashr_i32 s5, s4, 31
	s_lshl_b64 s[70:71], s[4:5], 7
	s_add_u32 s5, s22, s70
	s_addc_u32 s72, s23, s71
	s_add_u32 s70, s20, s70
	s_addc_u32 s71, s21, s71
	s_add_i32 s92, 0, 0x10000
	s_cmp_eq_u32 s53, s55
	s_cselect_b32 s73, s26, s72
	s_cselect_b32 s72, s17, s5
	s_cselect_b32 s71, s49, s71
	s_cselect_b32 s70, s27, s70
	s_add_i32 s5, 0, 0x14000
	v_add_u32_e32 v14, s92, v184
	v_add_u32_e32 v30, s5, v184
	ds_read_b128 v[2:5], v14
	ds_read_b128 v[6:9], v14 offset:1024
	ds_read_b128 v[10:13], v14 offset:2048
	ds_read_b128 v[14:17], v14 offset:3072
	ds_read_b128 v[18:21], v30
	ds_read_b128 v[22:25], v30 offset:1024
	ds_read_b128 v[26:29], v30 offset:2048
	ds_read_b128 v[30:33], v30 offset:3072
	s_add_u32 s55, s22, s90
	s_addc_u32 s91, s23, s91
	s_add_u32 s90, s55, 0x80000
	s_addc_u32 s91, s91, 0
	v_lshl_add_u64 v[242:243], s[90:91], 0, v[172:173]
	s_add_i32 m0, s19, 0xc000
	ds_read_b128 v[174:177], v216
	ds_read_b128 v[178:181], v216 offset:1024
	ds_read_b128 v[218:221], v216 offset:2048
	ds_read_b128 v[222:225], v216 offset:3072
	ds_read_b128 v[226:229], v216 offset:4096
	ds_read_b128 v[230:233], v216 offset:5120
	ds_read_b128 v[234:237], v216 offset:6144
	ds_read_b128 v[238:241], v216 offset:7168
	global_load_lds_dwordx4 v[242:243], off
	v_lshl_add_u64 v[242:243], s[90:91], 0, v[168:169]
	s_add_i32 m0, s19, 0xe000
	s_nop 0
	global_load_lds_dwordx4 v[242:243], off
	s_waitcnt vmcnt(8)
	s_barrier
	s_setprio 1
	s_waitcnt lgkmcnt(0)
	v_mfma_f32_16x16x128_f8f6f4 v[158:161], v[2:9], v[174:181], v[158:161]
	v_mfma_f32_16x16x128_f8f6f4 v[154:157], v[10:17], v[174:181], v[154:157]
	v_mfma_f32_16x16x128_f8f6f4 v[150:153], v[2:9], v[218:225], v[150:153]
	v_mfma_f32_16x16x128_f8f6f4 v[146:149], v[10:17], v[218:225], v[146:149]
	v_mfma_f32_16x16x128_f8f6f4 v[142:145], v[2:9], v[226:233], v[142:145]
	v_mfma_f32_16x16x128_f8f6f4 v[138:141], v[10:17], v[226:233], v[138:141]
	v_mfma_f32_16x16x128_f8f6f4 v[134:137], v[2:9], v[234:241], v[134:137]
	v_mfma_f32_16x16x128_f8f6f4 v[130:133], v[10:17], v[234:241], v[130:133]
	s_setprio 0
	s_setprio 1
	v_mfma_f32_16x16x128_f8f6f4 v[126:129], v[18:25], v[174:181], v[126:129]
	v_mfma_f32_16x16x128_f8f6f4 v[122:125], v[26:33], v[174:181], v[122:125]
	v_mfma_f32_16x16x128_f8f6f4 v[118:121], v[18:25], v[218:225], v[118:121]
	v_mfma_f32_16x16x128_f8f6f4 v[114:117], v[26:33], v[218:225], v[114:117]
	v_mfma_f32_16x16x128_f8f6f4 v[110:113], v[18:25], v[226:233], v[110:113]
	v_mfma_f32_16x16x128_f8f6f4 v[106:109], v[26:33], v[226:233], v[106:109]
	v_mfma_f32_16x16x128_f8f6f4 v[102:105], v[18:25], v[234:241], v[102:105]
	v_mfma_f32_16x16x128_f8f6f4 v[98:101], v[26:33], v[234:241], v[98:101]
	s_setprio 0
	s_barrier
	s_add_i32 s55, s92, s45
	v_lshl_add_u64 v[174:175], s[70:71], 0, v[170:171]
	s_mov_b32 m0, s55
	ds_read_b128 v[218:221], v216 offset:16384
	ds_read_b128 v[222:225], v216 offset:17408
	ds_read_b128 v[226:229], v216 offset:18432
	ds_read_b128 v[230:233], v216 offset:19456
	ds_read_b128 v[234:237], v216 offset:20480
	ds_read_b128 v[238:241], v216 offset:21504
	ds_read_b128 v[242:245], v216 offset:22528
	ds_read_b128 v[246:249], v216 offset:23552
	global_load_lds_dwordx4 v[174:175], off
	s_add_i32 m0, s55, 0x2000
	s_add_u32 s90, s70, 0x80000
	v_lshl_add_u64 v[176:177], s[70:71], 0, v[166:167]
	s_addc_u32 s91, s71, 0
	s_add_i32 s5, s5, s45
	global_load_lds_dwordx4 v[176:177], off
	v_lshl_add_u64 v[178:179], s[90:91], 0, v[170:171]
	s_mov_b32 m0, s5
	v_lshl_add_u64 v[180:181], s[72:73], 0, v[168:169]
	global_load_lds_dwordx4 v[178:179], off
	v_lshl_add_u64 v[178:179], s[90:91], 0, v[166:167]
	s_add_i32 m0, s5, 0x2000
	s_nop 0
	global_load_lds_dwordx4 v[178:179], off
	v_lshl_add_u64 v[178:179], s[72:73], 0, v[172:173]
	s_mov_b32 m0, s19
	s_nop 0
	global_load_lds_dwordx4 v[178:179], off
	s_mov_b32 m0, s47
	s_nop 0
	global_load_lds_dwordx4 v[180:181], off
	s_waitcnt vmcnt(8)
	s_barrier
	s_setprio 1
	s_waitcnt lgkmcnt(0)
	v_mfma_f32_16x16x128_f8f6f4 v[94:97], v[2:9], v[218:225], v[94:97]
	v_mfma_f32_16x16x128_f8f6f4 v[90:93], v[10:17], v[218:225], v[90:93]
	v_mfma_f32_16x16x128_f8f6f4 v[86:89], v[2:9], v[226:233], v[86:89]
	v_mfma_f32_16x16x128_f8f6f4 v[82:85], v[10:17], v[226:233], v[82:85]
	v_mfma_f32_16x16x128_f8f6f4 v[78:81], v[2:9], v[234:241], v[78:81]
	v_mfma_f32_16x16x128_f8f6f4 v[74:77], v[10:17], v[234:241], v[74:77]
	v_mfma_f32_16x16x128_f8f6f4 v[70:73], v[2:9], v[242:249], v[70:73]
	v_mfma_f32_16x16x128_f8f6f4 v[66:69], v[10:17], v[242:249], v[66:69]
	s_setprio 0
	s_setprio 1
	v_mfma_f32_16x16x128_f8f6f4 v[62:65], v[18:25], v[218:225], v[62:65]
	v_mfma_f32_16x16x128_f8f6f4 v[58:61], v[26:33], v[218:225], v[58:61]
	v_mfma_f32_16x16x128_f8f6f4 v[54:57], v[18:25], v[226:233], v[54:57]
	v_mfma_f32_16x16x128_f8f6f4 v[50:53], v[26:33], v[226:233], v[50:53]
	v_mfma_f32_16x16x128_f8f6f4 v[46:49], v[18:25], v[234:241], v[46:49]
	v_mfma_f32_16x16x128_f8f6f4 v[42:45], v[26:33], v[234:241], v[42:45]
	v_mfma_f32_16x16x128_f8f6f4 v[38:41], v[18:25], v[242:249], v[38:41]
	v_mfma_f32_16x16x128_f8f6f4 v[34:37], v[26:33], v[242:249], v[34:37]
	s_setprio 0
	s_barrier
; #define PG8_STAGE(bufoff, gbase, voff) do { if constexpr (DIAG >= 1) break; _Pragma("unroll") for (int _i = 0; _i < 2; ++_i) \
;         __builtin_amdgcn_global_load_lds((const unsigned*)((const char*)(gbase) + (voff)[_i]), (PG8_LAS unsigned*)(lds + (bufoff) + ldsw + _i * 8192), 16, 0, 0); } while (0)
; #define PG8_LDA(dst, b, h) do { if constexpr (DIAG == 2 || DIAG == 3) break; _Pragma("unroll") for (int m = 0; m < 4; ++m) _Pragma("unroll") for (int k = 0; k < 2; ++k) dst[m][k] = *(const PG8_LAS bf16x8*)(lds + PG8_SA(b, h) + aoff + m * 2048 + k * 1024); } while (0)
; #define PG8_WAIT_V(n) asm volatile("s_waitcnt vmcnt(" #n ")" ::: "memory")
; #define PG8_WAIT_L(n) asm volatile("s_waitcnt lgkmcnt(" #n ")" ::: "memory")
; #define PG8_BAR __builtin_amdgcn_s_barrier()
; #define PG8_LP_OFF __builtin_amdgcn_s_setprio(0)
;     ...
;         for (int t = kb; t < ke; t += 2) {
;             const bool last = (t == ke - 2);
;             const char* a1 = cA + (size_t)(t + 1) * kstep;
;             const char* a2 = last ? nA : cA + (size_t)(t + 2) * kstep; const char* b2 = last ? nB : cB + (size_t)(t + 2) * kstep;
;             const char* a3 = a2 + kstep; const char* b3 = b2 + kstep;
;             if (last && has_next) S.a_ready(nxt);
;             if constexpr (SP2) {
;             PG8_LP_ON; PG8_LDB(B0, 0, 0); PG8_LDB(B1, 0, 1); PG8_SCHED; PG8_LDA(At, 0, 0); PG8_STAGE(PG8_SA(1, 1), a1 + hstep, voffA);
;             PG8_LP_OFF; PG8_WAIT_V(8); PG8_WAIT_L(0); PG8_BAR; PG8_MMA(0, 0, At, B0); PG8_MMA(0, 1, At, B1); PG8_BAR; PG8_SCHED;
;             PG8_LP_ON; PG8_LDA(At, 0, 1); PG8_STAGE(PG8_SB(0, 0), b2, voffB); PG8_STAGE(PG8_SB(0, 1), b2 + hstep, voffB); PG8_STAGE(PG8_SA(0, 0), a2, voffA);
;             PG8_LP_OFF; PG8_WAIT_V(8); PG8_WAIT_L(0); PG8_BAR; PG8_MMA(1, 0, At, B0); PG8_MMA(1, 1, At, B1); PG8_BAR; PG8_SCHED;
;             PG8_LP_ON; PG8_LDB(B0, 1, 0); PG8_LDB(B1, 1, 1); PG8_SCHED; PG8_LDA(At, 1, 0); PG8_STAGE(PG8_SA(0, 1), a2 + hstep, voffA);
;             PG8_LP_OFF; PG8_WAIT_V(8); PG8_WAIT_L(0); PG8_BAR; PG8_MMA(0, 0, At, B0); PG8_MMA(0, 1, At, B1); PG8_BAR; PG8_SCHED;
;             PG8_LP_ON; PG8_LDA(At, 1, 1); PG8_STAGE(PG8_SB(1, 0), b3, voffB); PG8_STAGE(PG8_SB(1, 1), b3 + hstep, voffB); PG8_STAGE(PG8_SA(1, 0), a3, voffA);
;             PG8_LP_OFF; PG8_WAIT_V(8); PG8_WAIT_L(0); PG8_BAR; PG8_MMA(1, 0, At, B0); PG8_MMA(1, 1, At, B1); PG8_BAR; PG8_SCHED;
	s_add_i32 s5, 0, 0x18000
	s_add_i32 s55, 0, 0x1c000
	v_add_u32_e32 v2, s5, v184
	v_add_u32_e32 v6, s55, v184
	ds_read_b128 v[26:29], v2
	ds_read_b128 v[30:33], v2 offset:1024
	ds_read_b128 v[18:21], v2 offset:2048
	ds_read_b128 v[22:25], v2 offset:3072
	ds_read_b128 v[10:13], v6
	ds_read_b128 v[14:17], v6 offset:1024
	ds_read_b128 v[2:5], v6 offset:2048
	ds_read_b128 v[6:9], v6 offset:3072
	s_add_u32 s72, s72, 0x80000
	s_addc_u32 s73, s73, 0
	s_mov_b32 m0, s74
	v_lshl_add_u64 v[250:251], s[72:73], 0, v[172:173]
	ds_read_b128 v[218:221], v216 offset:32768
	ds_read_b128 v[222:225], v216 offset:33792
	ds_read_b128 v[226:229], v216 offset:34816
	ds_read_b128 v[230:233], v216 offset:35840
	ds_read_b128 v[234:237], v216 offset:36864
	ds_read_b128 v[238:241], v216 offset:37888
	ds_read_b128 v[242:245], v216 offset:38912
	ds_read_b128 v[246:249], v216 offset:39936
	global_load_lds_dwordx4 v[250:251], off
	v_lshl_add_u64 v[250:251], s[72:73], 0, v[168:169]
	s_mov_b32 m0, s75
	s_nop 0
	global_load_lds_dwordx4 v[250:251], off
	s_waitcnt vmcnt(8)
	s_barrier
	s_setprio 1
	s_waitcnt lgkmcnt(0)
	v_mfma_f32_16x16x128_f8f6f4 v[158:161], v[26:33], v[218:225], v[158:161]
	v_mfma_f32_16x16x128_f8f6f4 v[154:157], v[18:25], v[218:225], v[154:157]
	v_mfma_f32_16x16x128_f8f6f4 v[150:153], v[26:33], v[226:233], v[150:153]
	v_mfma_f32_16x16x128_f8f6f4 v[146:149], v[18:25], v[226:233], v[146:149]
	v_mfma_f32_16x16x128_f8f6f4 v[142:145], v[26:33], v[234:241], v[142:145]
	v_mfma_f32_16x16x128_f8f6f4 v[138:141], v[18:25], v[234:241], v[138:141]
	v_mfma_f32_16x16x128_f8f6f4 v[134:137], v[26:33], v[242:249], v[134:137]
	v_mfma_f32_16x16x128_f8f6f4 v[130:133], v[18:25], v[242:249], v[130:133]
	s_setprio 0
	s_setprio 1
	v_mfma_f32_16x16x128_f8f6f4 v[126:129], v[10:17], v[218:225], v[126:129]
	v_mfma_f32_16x16x128_f8f6f4 v[122:125], v[2:9], v[218:225], v[122:125]
	v_mfma_f32_16x16x128_f8f6f4 v[118:121], v[10:17], v[226:233], v[118:121]
	v_mfma_f32_16x16x128_f8f6f4 v[114:117], v[2:9], v[226:233], v[114:117]
	v_mfma_f32_16x16x128_f8f6f4 v[110:113], v[10:17], v[234:241], v[110:113]
	v_mfma_f32_16x16x128_f8f6f4 v[106:109], v[2:9], v[234:241], v[106:109]
	v_mfma_f32_16x16x128_f8f6f4 v[102:105], v[10:17], v[242:249], v[102:105]
	v_mfma_f32_16x16x128_f8f6f4 v[98:101], v[2:9], v[242:249], v[98:101]
	s_setprio 0
	s_barrier
	s_add_i32 s5, s5, s45
	v_lshl_add_u64 v[174:175], v[174:175], 0, s[40:41]
	s_mov_b32 m0, s5
	ds_read_b128 v[218:221], v216 offset:49152
	ds_read_b128 v[222:225], v216 offset:50176
	ds_read_b128 v[226:229], v216 offset:51200
	ds_read_b128 v[230:233], v216 offset:52224
	ds_read_b128 v[234:237], v216 offset:53248
	ds_read_b128 v[238:241], v216 offset:54272
	ds_read_b128 v[242:245], v216 offset:55296
	ds_read_b128 v[246:249], v216 offset:56320
	global_load_lds_dwordx4 v[174:175], off
	s_add_i32 m0, s5, 0x2000
	s_add_u32 s70, s70, 0x80080
	v_lshl_add_u64 v[174:175], v[176:177], 0, s[40:41]
	s_addc_u32 s71, s71, 0
	s_add_i32 s5, s55, s45
	global_load_lds_dwordx4 v[174:175], off
	v_lshl_add_u64 v[174:175], s[70:71], 0, v[170:171]
	s_mov_b32 m0, s5
	s_nop 0
	global_load_lds_dwordx4 v[174:175], off
	v_lshl_add_u64 v[174:175], s[70:71], 0, v[166:167]
	s_add_i32 m0, s5, 0x2000
	s_nop 0
	global_load_lds_dwordx4 v[174:175], off
	v_lshl_add_u64 v[174:175], v[178:179], 0, s[40:41]
	s_mov_b32 m0, s82
	s_nop 0
	global_load_lds_dwordx4 v[174:175], off
	v_lshl_add_u64 v[174:175], v[180:181], 0, s[40:41]
	s_mov_b32 m0, s83
	s_nop 0
	global_load_lds_dwordx4 v[174:175], off
	s_waitcnt vmcnt(8)
	s_barrier
	s_setprio 1
	s_waitcnt lgkmcnt(0)
	v_mfma_f32_16x16x128_f8f6f4 v[94:97], v[26:33], v[218:225], v[94:97]
	v_mfma_f32_16x16x128_f8f6f4 v[90:93], v[18:25], v[218:225], v[90:93]
	v_mfma_f32_16x16x128_f8f6f4 v[86:89], v[26:33], v[226:233], v[86:89]
	v_mfma_f32_16x16x128_f8f6f4 v[82:85], v[18:25], v[226:233], v[82:85]
	v_mfma_f32_16x16x128_f8f6f4 v[78:81], v[26:33], v[234:241], v[78:81]
	v_mfma_f32_16x16x128_f8f6f4 v[74:77], v[18:25], v[234:241], v[74:77]
	v_mfma_f32_16x16x128_f8f6f4 v[70:73], v[26:33], v[242:249], v[70:73]
	v_mfma_f32_16x16x128_f8f6f4 v[66:69], v[18:25], v[242:249], v[66:69]
	s_setprio 0
	s_setprio 1
	v_mfma_f32_16x16x128_f8f6f4 v[62:65], v[10:17], v[218:225], v[62:65]
	v_mfma_f32_16x16x128_f8f6f4 v[58:61], v[2:9], v[218:225], v[58:61]
	v_mfma_f32_16x16x128_f8f6f4 v[54:57], v[10:17], v[226:233], v[54:57]
	v_mfma_f32_16x16x128_f8f6f4 v[50:53], v[2:9], v[226:233], v[50:53]
	v_mfma_f32_16x16x128_f8f6f4 v[46:49], v[10:17], v[234:241], v[46:49]
	v_mfma_f32_16x16x128_f8f6f4 v[42:45], v[2:9], v[234:241], v[42:45]
	v_mfma_f32_16x16x128_f8f6f4 v[38:41], v[10:17], v[242:249], v[38:41]
	v_mfma_f32_16x16x128_f8f6f4 v[34:37], v[2:9], v[242:249], v[34:37]
	s_setprio 0
	s_barrier
	s_cmp_ge_i32 s4, s79
	s_mov_b32 s55, s4
	s_cbranch_scc0 .LBB0_918

; #define PG8_STAGE(bufoff, gbase, voff) do { if constexpr (DIAG >= 1) break; _Pragma("unroll") for (int _i = 0; _i < 2; ++_i) \
;         __builtin_amdgcn_global_load_lds((const unsigned*)((const char*)(gbase) + (voff)[_i]), (PG8_LAS unsigned*)(lds + (bufoff) + ldsw + _i * 8192), 16, 0, 0); } while (0)
; #define PG8_LDA(dst, b, h) do { if constexpr (DIAG == 2 || DIAG == 3) break; _Pragma("unroll") for (int m = 0; m < 4; ++m) _Pragma("unroll") for (int k = 0; k < 2; ++k) dst[m][k] = *(const PG8_LAS bf16x8*)(lds + PG8_SA(b, h) + aoff + m * 2048 + k * 1024); } while (0)
; #define PG8_LDB(dst, b, h) do { if constexpr (DIAG == 2 || DIAG == 3) break; _Pragma("unroll") for (int n = 0; n < 2; ++n) _Pragma("unroll") for (int k = 0; k < 2; ++k) dst[n][k] = *(const PG8_LAS bf16x8*)(lds + PG8_SB(b, h) + boff + n * 2048 + k * 1024); } while (0)
; #define PG8_WAIT_V(n) asm volatile("s_waitcnt vmcnt(" #n ")" ::: "memory")
; #define PG8_WAIT_L(n) asm volatile("s_waitcnt lgkmcnt(" #n ")" ::: "memory")
; #define PG8_BAR __builtin_amdgcn_s_barrier()
; #define PG8_LP_ON __builtin_amdgcn_s_setprio(PG8_LOADPRIO)
; #define PG8_LP_OFF __builtin_amdgcn_s_setprio(0)
; #define PG8_LP_ON do {} while (0)
; #define PG8_LP_OFF do {} while (0)
; #define PG8_SCHED __builtin_amdgcn_sched_barrier(0)
;     ...
;             PG8_LP_ON; PG8_LDB(B0, 0, 0); PG8_LDB(B1, 0, 1); PG8_SCHED; PG8_LDA(At, 0, 0); PG8_STAGE(PG8_SA(1, 1), a1 + hstep, voffA);
;             PG8_LP_OFF; PG8_WAIT_V(8); PG8_WAIT_L(0); PG8_BAR; PG8_MMA(0, 0, At, B0); PG8_MMA(0, 1, At, B1); PG8_BAR; PG8_SCHED;
;             PG8_LP_ON; PG8_LDA(At, 0, 1); PG8_STAGE(PG8_SB(0, 0), b2, voffB); PG8_STAGE(PG8_SB(0, 1), b2 + hstep, voffB); PG8_STAGE(PG8_SA(0, 0), a2, voffA);
;             PG8_LP_OFF; PG8_WAIT_V(8); PG8_WAIT_L(0); PG8_BAR; PG8_MMA(1, 0, At, B0); PG8_MMA(1, 1, At, B1); PG8_BAR; PG8_SCHED;
.LBB0_1034:
	s_add_i32 s6, s8, 1
	s_ashr_i32 s7, s6, 31
	s_lshl_b64 s[88:89], s[6:7], 7
	s_add_i32 s6, s8, 2
	s_ashr_i32 s7, s6, 31
	s_lshl_b64 s[60:61], s[6:7], 7
	s_add_u32 s7, s24, s60
	s_addc_u32 s9, s25, s61
	s_add_u32 s90, s22, s60
	s_addc_u32 s91, s23, s61
	s_add_i32 s92, 0, 0x10000
	s_cmp_eq_u32 s87, s8
	s_cselect_b32 s61, s26, s9
	s_cselect_b32 s60, s19, s7
	s_cselect_b32 s9, s47, s91
	s_cselect_b32 s8, s27, s90
	s_add_i32 s7, 0, 0x14000
	v_add_u32_e32 v14, s92, v181
	v_add_u32_e32 v30, s7, v181
	ds_read_b128 v[2:5], v14
	ds_read_b128 v[6:9], v14 offset:1024
	ds_read_b128 v[10:13], v14 offset:2048
	ds_read_b128 v[14:17], v14 offset:3072
	ds_read_b128 v[18:21], v30
	ds_read_b128 v[22:25], v30 offset:1024
	ds_read_b128 v[26:29], v30 offset:2048
	ds_read_b128 v[30:33], v30 offset:3072
	s_add_u32 s88, s24, s88
	s_addc_u32 s89, s25, s89
	s_add_u32 s88, s88, 0x158000
	s_addc_u32 s89, s89, 0
	v_lshl_add_u64 v[238:239], s[88:89], 0, v[166:167]
	s_add_i32 m0, s66, 0xc000
	ds_read_b128 v[172:175], v213
	ds_read_b128 v[176:179], v213 offset:1024
	ds_read_b128 v[214:217], v213 offset:2048
	ds_read_b128 v[218:221], v213 offset:3072
	ds_read_b128 v[222:225], v213 offset:4096
	ds_read_b128 v[226:229], v213 offset:5120
	ds_read_b128 v[230:233], v213 offset:6144
	ds_read_b128 v[234:237], v213 offset:7168
	global_load_lds_dwordx4 v[238:239], off
	v_lshl_add_u64 v[238:239], s[88:89], 0, v[168:169]
	s_add_i32 m0, s66, 0xe000
	s_nop 0
	global_load_lds_dwordx4 v[238:239], off
	s_waitcnt vmcnt(8)
	s_barrier
	s_setprio 1
	s_waitcnt lgkmcnt(0)
	v_mfma_f32_16x16x128_f8f6f4 v[158:161], v[2:9], v[172:179], v[158:161]
	v_mfma_f32_16x16x128_f8f6f4 v[154:157], v[10:17], v[172:179], v[154:157]
	v_mfma_f32_16x16x128_f8f6f4 v[150:153], v[2:9], v[214:221], v[150:153]
	v_mfma_f32_16x16x128_f8f6f4 v[146:149], v[10:17], v[214:221], v[146:149]
	v_mfma_f32_16x16x128_f8f6f4 v[142:145], v[2:9], v[222:229], v[142:145]
	v_mfma_f32_16x16x128_f8f6f4 v[138:141], v[10:17], v[222:229], v[138:141]
	v_mfma_f32_16x16x128_f8f6f4 v[134:137], v[2:9], v[230:237], v[134:137]
	v_mfma_f32_16x16x128_f8f6f4 v[130:133], v[10:17], v[230:237], v[130:133]
	s_setprio 0
	s_setprio 1
	v_mfma_f32_16x16x128_f8f6f4 v[126:129], v[18:25], v[172:179], v[126:129]
	v_mfma_f32_16x16x128_f8f6f4 v[122:125], v[26:33], v[172:179], v[122:125]
	v_mfma_f32_16x16x128_f8f6f4 v[118:121], v[18:25], v[214:221], v[118:121]
	v_mfma_f32_16x16x128_f8f6f4 v[114:117], v[26:33], v[214:221], v[114:117]
	v_mfma_f32_16x16x128_f8f6f4 v[110:113], v[18:25], v[222:229], v[110:113]
	v_mfma_f32_16x16x128_f8f6f4 v[106:109], v[26:33], v[222:229], v[106:109]
	v_mfma_f32_16x16x128_f8f6f4 v[102:105], v[18:25], v[230:237], v[102:105]
	v_mfma_f32_16x16x128_f8f6f4 v[98:101], v[26:33], v[230:237], v[98:101]
	s_setprio 0
	s_barrier
	s_add_i32 s88, s92, s65
	v_lshl_add_u64 v[172:173], s[8:9], 0, v[166:167]
	s_mov_b32 m0, s88
	ds_read_b128 v[214:217], v213 offset:16384
	ds_read_b128 v[218:221], v213 offset:17408
	ds_read_b128 v[222:225], v213 offset:18432
	ds_read_b128 v[226:229], v213 offset:19456
	ds_read_b128 v[230:233], v213 offset:20480
	ds_read_b128 v[234:237], v213 offset:21504
	ds_read_b128 v[238:241], v213 offset:22528
	ds_read_b128 v[242:245], v213 offset:23552
	global_load_lds_dwordx4 v[172:173], off
	s_add_i32 m0, s88, 0x2000
	s_add_u32 s88, s8, 0x158000
	v_lshl_add_u64 v[174:175], s[8:9], 0, v[168:169]
	s_addc_u32 s89, s9, 0
	s_add_i32 s7, s7, s65
	global_load_lds_dwordx4 v[174:175], off
	v_lshl_add_u64 v[176:177], s[88:89], 0, v[166:167]
	s_mov_b32 m0, s7
	v_lshl_add_u64 v[178:179], s[60:61], 0, v[168:169]
	global_load_lds_dwordx4 v[176:177], off
	v_lshl_add_u64 v[176:177], s[88:89], 0, v[168:169]
	s_add_i32 m0, s7, 0x2000
	s_nop 0
	global_load_lds_dwordx4 v[176:177], off
	v_lshl_add_u64 v[176:177], s[60:61], 0, v[166:167]
	s_mov_b32 m0, s66
	s_nop 0
	global_load_lds_dwordx4 v[176:177], off
	s_mov_b32 m0, s67
	s_nop 0
	global_load_lds_dwordx4 v[178:179], off
	s_waitcnt vmcnt(8)
	s_barrier
	s_setprio 1
	s_waitcnt lgkmcnt(0)
	v_mfma_f32_16x16x128_f8f6f4 v[94:97], v[2:9], v[214:221], v[94:97]
	v_mfma_f32_16x16x128_f8f6f4 v[90:93], v[10:17], v[214:221], v[90:93]
	v_mfma_f32_16x16x128_f8f6f4 v[86:89], v[2:9], v[222:229], v[86:89]
	v_mfma_f32_16x16x128_f8f6f4 v[82:85], v[10:17], v[222:229], v[82:85]
	v_mfma_f32_16x16x128_f8f6f4 v[78:81], v[2:9], v[230:237], v[78:81]
	v_mfma_f32_16x16x128_f8f6f4 v[74:77], v[10:17], v[230:237], v[74:77]
	v_mfma_f32_16x16x128_f8f6f4 v[70:73], v[2:9], v[238:245], v[70:73]
	v_mfma_f32_16x16x128_f8f6f4 v[66:69], v[10:17], v[238:245], v[66:69]
	s_setprio 0
	s_setprio 1
	v_mfma_f32_16x16x128_f8f6f4 v[62:65], v[18:25], v[214:221], v[62:65]
	v_mfma_f32_16x16x128_f8f6f4 v[58:61], v[26:33], v[214:221], v[58:61]
	v_mfma_f32_16x16x128_f8f6f4 v[54:57], v[18:25], v[222:229], v[54:57]
	v_mfma_f32_16x16x128_f8f6f4 v[50:53], v[26:33], v[222:229], v[50:53]
	v_mfma_f32_16x16x128_f8f6f4 v[46:49], v[18:25], v[230:237], v[46:49]
	v_mfma_f32_16x16x128_f8f6f4 v[42:45], v[26:33], v[230:237], v[42:45]
	v_mfma_f32_16x16x128_f8f6f4 v[38:41], v[18:25], v[238:245], v[38:41]
	v_mfma_f32_16x16x128_f8f6f4 v[34:37], v[26:33], v[238:245], v[34:37]
	s_setprio 0
	s_barrier
; #define PG8_STAGE(bufoff, gbase, voff) do { if constexpr (DIAG >= 1) break; _Pragma("unroll") for (int _i = 0; _i < 2; ++_i) \
;         __builtin_amdgcn_global_load_lds((const unsigned*)((const char*)(gbase) + (voff)[_i]), (PG8_LAS unsigned*)(lds + (bufoff) + ldsw + _i * 8192), 16, 0, 0); } while (0)
; #define PG8_LDA(dst, b, h) do { if constexpr (DIAG == 2 || DIAG == 3) break; _Pragma("unroll") for (int m = 0; m < 4; ++m) _Pragma("unroll") for (int k = 0; k < 2; ++k) dst[m][k] = *(const PG8_LAS bf16x8*)(lds + PG8_SA(b, h) + aoff + m * 2048 + k * 1024); } while (0)
; #define PG8_LDB(dst, b, h) do { if constexpr (DIAG == 2 || DIAG == 3) break; _Pragma("unroll") for (int n = 0; n < 2; ++n) _Pragma("unroll") for (int k = 0; k < 2; ++k) dst[n][k] = *(const PG8_LAS bf16x8*)(lds + PG8_SB(b, h) + boff + n * 2048 + k * 1024); } while (0)
; #define PG8_WAIT_V(n) asm volatile("s_waitcnt vmcnt(" #n ")" ::: "memory")
; #define PG8_WAIT_L(n) asm volatile("s_waitcnt lgkmcnt(" #n ")" ::: "memory")
; #define PG8_BAR __builtin_amdgcn_s_barrier()
; #define PG8_LP_ON __builtin_amdgcn_s_setprio(PG8_LOADPRIO)
; #define PG8_LP_OFF __builtin_amdgcn_s_setprio(0)
; #define PG8_LP_ON do {} while (0)
; #define PG8_LP_OFF do {} while (0)
; #define PG8_SCHED __builtin_amdgcn_sched_barrier(0)
;     ...
;             PG8_LP_ON; PG8_LDB(B0, 1, 0); PG8_LDB(B1, 1, 1); PG8_SCHED; PG8_LDA(At, 1, 0); PG8_STAGE(PG8_SA(0, 1), a2 + hstep, voffA);
;             PG8_LP_OFF; PG8_WAIT_V(8); PG8_WAIT_L(0); PG8_BAR; PG8_MMA(0, 0, At, B0); PG8_MMA(0, 1, At, B1); PG8_BAR; PG8_SCHED;
;             PG8_LP_ON; PG8_LDA(At, 1, 1); PG8_STAGE(PG8_SB(1, 0), b3, voffB); PG8_STAGE(PG8_SB(1, 1), b3 + hstep, voffB); PG8_STAGE(PG8_SA(1, 0), a3, voffA);
;             PG8_LP_OFF; PG8_WAIT_V(8); PG8_WAIT_L(0); PG8_BAR; PG8_MMA(1, 0, At, B0); PG8_MMA(1, 1, At, B1); PG8_BAR; PG8_SCHED;
	s_add_i32 s7, 0, 0x18000
	s_add_i32 s88, 0, 0x1c000
	v_add_u32_e32 v2, s7, v181
	v_add_u32_e32 v6, s88, v181
	ds_read_b128 v[26:29], v2
	ds_read_b128 v[30:33], v2 offset:1024
	ds_read_b128 v[18:21], v2 offset:2048
	ds_read_b128 v[22:25], v2 offset:3072
	ds_read_b128 v[10:13], v6
	ds_read_b128 v[14:17], v6 offset:1024
	ds_read_b128 v[2:5], v6 offset:2048
	ds_read_b128 v[6:9], v6 offset:3072
	s_add_u32 s60, s60, 0x158000
	s_addc_u32 s61, s61, 0
	s_mov_b32 m0, s70
	v_lshl_add_u64 v[246:247], s[60:61], 0, v[166:167]
	ds_read_b128 v[214:217], v213 offset:32768
	ds_read_b128 v[218:221], v213 offset:33792
	ds_read_b128 v[222:225], v213 offset:34816
	ds_read_b128 v[226:229], v213 offset:35840
	ds_read_b128 v[230:233], v213 offset:36864
	ds_read_b128 v[234:237], v213 offset:37888
	ds_read_b128 v[238:241], v213 offset:38912
	ds_read_b128 v[242:245], v213 offset:39936
	global_load_lds_dwordx4 v[246:247], off
	v_lshl_add_u64 v[246:247], s[60:61], 0, v[168:169]
	s_mov_b32 m0, s71
	s_nop 0
	global_load_lds_dwordx4 v[246:247], off
	s_waitcnt vmcnt(8)
	s_barrier
	s_setprio 1
	s_waitcnt lgkmcnt(0)
	v_mfma_f32_16x16x128_f8f6f4 v[158:161], v[26:33], v[214:221], v[158:161]
	v_mfma_f32_16x16x128_f8f6f4 v[154:157], v[18:25], v[214:221], v[154:157]
	v_mfma_f32_16x16x128_f8f6f4 v[150:153], v[26:33], v[222:229], v[150:153]
	v_mfma_f32_16x16x128_f8f6f4 v[146:149], v[18:25], v[222:229], v[146:149]
	v_mfma_f32_16x16x128_f8f6f4 v[142:145], v[26:33], v[230:237], v[142:145]
	v_mfma_f32_16x16x128_f8f6f4 v[138:141], v[18:25], v[230:237], v[138:141]
	v_mfma_f32_16x16x128_f8f6f4 v[134:137], v[26:33], v[238:245], v[134:137]
	v_mfma_f32_16x16x128_f8f6f4 v[130:133], v[18:25], v[238:245], v[130:133]
	s_setprio 0
	s_setprio 1
	v_mfma_f32_16x16x128_f8f6f4 v[126:129], v[10:17], v[214:221], v[126:129]
	v_mfma_f32_16x16x128_f8f6f4 v[122:125], v[2:9], v[214:221], v[122:125]
	v_mfma_f32_16x16x128_f8f6f4 v[118:121], v[10:17], v[222:229], v[118:121]
	v_mfma_f32_16x16x128_f8f6f4 v[114:117], v[2:9], v[222:229], v[114:117]
	v_mfma_f32_16x16x128_f8f6f4 v[110:113], v[10:17], v[230:237], v[110:113]
	v_mfma_f32_16x16x128_f8f6f4 v[106:109], v[2:9], v[230:237], v[106:109]
	v_mfma_f32_16x16x128_f8f6f4 v[102:105], v[10:17], v[238:245], v[102:105]
	v_mfma_f32_16x16x128_f8f6f4 v[98:101], v[2:9], v[238:245], v[98:101]
	s_setprio 0
	s_barrier
	s_add_i32 s7, s7, s65
	v_lshl_add_u64 v[172:173], v[172:173], 0, s[40:41]
	s_mov_b32 m0, s7
	ds_read_b128 v[214:217], v213 offset:49152
	ds_read_b128 v[218:221], v213 offset:50176
	ds_read_b128 v[222:225], v213 offset:51200
	ds_read_b128 v[226:229], v213 offset:52224
	ds_read_b128 v[230:233], v213 offset:53248
	ds_read_b128 v[234:237], v213 offset:54272
	ds_read_b128 v[238:241], v213 offset:55296
	ds_read_b128 v[242:245], v213 offset:56320
	global_load_lds_dwordx4 v[172:173], off
	s_add_i32 m0, s7, 0x2000
	s_add_u32 s8, s8, 0x158080
	v_lshl_add_u64 v[172:173], v[174:175], 0, s[40:41]
	s_addc_u32 s9, s9, 0
	s_add_i32 s7, s88, s65
	global_load_lds_dwordx4 v[172:173], off
	v_lshl_add_u64 v[172:173], s[8:9], 0, v[166:167]
	s_mov_b32 m0, s7
	s_nop 0
	global_load_lds_dwordx4 v[172:173], off
	v_lshl_add_u64 v[172:173], s[8:9], 0, v[168:169]
	s_add_i32 m0, s7, 0x2000
	s_nop 0
	global_load_lds_dwordx4 v[172:173], off
	v_lshl_add_u64 v[172:173], v[176:177], 0, s[40:41]
	s_mov_b32 m0, s77
	s_nop 0
	global_load_lds_dwordx4 v[172:173], off
	v_lshl_add_u64 v[172:173], v[178:179], 0, s[40:41]
	s_mov_b32 m0, s78
	s_nop 0
	global_load_lds_dwordx4 v[172:173], off
	s_waitcnt vmcnt(8)
	s_barrier
	s_setprio 1
	s_waitcnt lgkmcnt(0)
	v_mfma_f32_16x16x128_f8f6f4 v[94:97], v[26:33], v[214:221], v[94:97]
	v_mfma_f32_16x16x128_f8f6f4 v[90:93], v[18:25], v[214:221], v[90:93]
	v_mfma_f32_16x16x128_f8f6f4 v[86:89], v[26:33], v[222:229], v[86:89]
	v_mfma_f32_16x16x128_f8f6f4 v[82:85], v[18:25], v[222:229], v[82:85]
	v_mfma_f32_16x16x128_f8f6f4 v[78:81], v[26:33], v[230:237], v[78:81]
	v_mfma_f32_16x16x128_f8f6f4 v[74:77], v[18:25], v[230:237], v[74:77]
	v_mfma_f32_16x16x128_f8f6f4 v[70:73], v[26:33], v[238:245], v[70:73]
	v_mfma_f32_16x16x128_f8f6f4 v[66:69], v[18:25], v[238:245], v[66:69]
	s_setprio 0
	s_setprio 1
	v_mfma_f32_16x16x128_f8f6f4 v[62:65], v[10:17], v[214:221], v[62:65]
	v_mfma_f32_16x16x128_f8f6f4 v[58:61], v[2:9], v[214:221], v[58:61]
	v_mfma_f32_16x16x128_f8f6f4 v[54:57], v[10:17], v[222:229], v[54:57]
	v_mfma_f32_16x16x128_f8f6f4 v[50:53], v[2:9], v[222:229], v[50:53]
	v_mfma_f32_16x16x128_f8f6f4 v[46:49], v[10:17], v[230:237], v[46:49]
	v_mfma_f32_16x16x128_f8f6f4 v[42:45], v[2:9], v[230:237], v[42:45]
	v_mfma_f32_16x16x128_f8f6f4 v[38:41], v[10:17], v[238:245], v[38:41]
	v_mfma_f32_16x16x128_f8f6f4 v[34:37], v[2:9], v[238:245], v[34:37]
	s_setprio 0
	s_barrier
	s_cmp_ge_i32 s6, s64
	s_mov_b32 s8, s6
	s_cbranch_scc0 .LBB0_1034
	v_readlane_b32 s94, v252, 39
	v_readlane_b32 s95, v252, 40
